# SK stored fragment-major (coalesced strip K loads) + hand-written scan
# speedup vs baseline: 1.0075x; 1.0075x over previous
; __device__ __forceinline__ unsigned cvt_pk_bf16(float lo, float hi) { unsigned r; asm volatile("v_cvt_pk_bf16_f32 %0, %1, %2" : "=v"(r) : "v"(lo), "v"(hi)); return r; }
;     __device__ __forceinline__ void operator()(const f32x4 (&acc)[2][2][4][2], const Unit& u, int wr, int wc, int fr, int fq) const {
;     ...
;                 for (int m = 0; m < 4; ++m) { const int row = row0 + ai * HALF + m * 16; const float rs = rsv[ai][m]; float sq = 0.f; f32x4 t[2][2];
; #pragma unroll
;                     for (int bj = 0; bj < 2; ++bj)
; #pragma unroll
;                         for (int n = 0; n < 2; ++n) { t[bj][n] = acc[ai][bj][m][n] * rs; sq += (t[bj][n][0] * t[bj][n][0] + t[bj][n][1] * t[bj][n][1]) + (t[bj][n][2] * t[bj][n][2] + t[bj][n][3] * t[bj][n][3]); }
;                     sq += __shfl_xor(sq, 16); sq += __shfl_xor(sq, 32);
;                     const float rn = 1.0f / sqrtf(sq * (1.0f / 64.0f) + 1e-6f);
; #pragma unroll
;                     for (int bj = 0; bj < 2; ++bj) { const f32x4 a = t[bj][0] * rn * gv[bj][0], b = t[bj][1] * rn * gv[bj][1];
;                         u32x4 w; w.x = cvt_pk_bf16(a[0], a[1]); w.y = cvt_pk_bf16(a[2], a[3]); w.z = cvt_pk_bf16(b[0], b[1]); w.w = cvt_pk_bf16(b[2], b[3]);
;                         *(u32x4*)(dst + (size_t)row * 512 + head * 64 + 32 * bj + 8 * fq) = w; } }
.LBB0_868:
	v_and_b32_e32 v129, 64, v188
	v_xor_b32_e32 v128, 16, v188
	v_add_u32_e32 v131, 64, v129
	v_cmp_lt_i32_e32 vcc, v128, v131
	s_waitcnt lgkmcnt(0)
	v_pk_mul_f32 v[142:143], v[126:127], v[170:171] op_sel_hi:[1,0]
	v_pk_mul_f32 v[172:173], v[124:125], v[170:171] op_sel_hi:[1,0]
	v_cndmask_b32_e32 v128, v188, v128, vcc
	v_pk_mul_f32 v[124:125], v[142:143], v[142:143]
	v_pk_mul_f32 v[126:127], v[172:173], v[172:173]
	v_pk_mul_f32 v[190:191], v[122:123], v[170:171] op_sel_hi:[1,0]
	v_pk_mul_f32 v[192:193], v[120:121], v[170:171] op_sel_hi:[1,0]
	v_pk_mul_f32 v[138:139], v[116:117], v[170:171] op_sel_hi:[1,0]
	v_lshlrev_b32_e32 v140, 2, v128
	v_pk_mov_b32 v[128:129], v[126:127], v[124:125] op_sel:[1,0]
	v_mov_b32_e32 v127, v125
	v_pk_mul_f32 v[120:121], v[190:191], v[190:191]
	v_pk_mul_f32 v[122:123], v[192:193], v[192:193]
	v_mul_f32_e32 v116, v138, v138
	v_pk_add_f32 v[124:125], v[128:129], v[126:127]
	v_pk_mov_b32 v[126:127], v[122:123], v[120:121] op_sel:[1,0]
	v_mov_b32_e32 v123, v121
	v_pk_mul_f32 v[136:137], v[118:119], v[170:171] op_sel_hi:[1,0]
	v_pk_fma_f32 v[116:117], v[138:139], v[138:139], v[116:117] op_sel_hi:[1,1,0]
	v_pk_add_f32 v[120:121], v[126:127], v[122:123]
	v_mul_f32_e32 v116, v136, v136
	v_pk_add_f32 v[124:125], v[124:125], v[124:125] op_sel_hi:[0,1]
	v_pk_add_f32 v[120:121], v[120:121], v[120:121] op_sel_hi:[0,1]
	v_pk_fma_f32 v[118:119], v[136:137], v[136:137], v[116:117] op_sel_hi:[1,1,0]
	v_pk_mul_f32 v[132:133], v[114:115], v[170:171] op_sel_hi:[1,0]
	v_pk_mul_f32 v[134:135], v[112:113], v[170:171] op_sel_hi:[1,0]
	v_mul_f32_e32 v124, v132, v132
	v_mul_f32_e32 v116, v134, v134
	v_mul_f32_e32 v118, v135, v135
	v_mul_f32_e32 v120, v133, v133
	v_pk_add_f32 v[112:113], v[116:117], v[118:119]
	v_pk_add_f32 v[114:115], v[124:125], v[120:121]
	s_cmp_eq_u32 s1, 4
	v_pk_add_f32 v[112:113], v[112:113], v[114:115]
	v_xor_b32_e32 v114, 32, v188
	v_add_f32_e32 v112, v112, v113
	ds_bpermute_b32 v113, v140, v112
	v_cmp_lt_i32_e32 vcc, v114, v131
	s_cselect_b64 s[4:5], -1, 0
	s_and_b64 s[4:5], s[4:5], exec
	v_cndmask_b32_e32 v114, v188, v114, vcc
	v_lshlrev_b32_e32 v141, 2, v114
	s_waitcnt lgkmcnt(0)
	v_add_f32_e32 v128, v112, v113
	ds_bpermute_b32 v129, v141, v128
	s_cselect_b32 s4, 0, 0x100
	s_mov_b32 s1, 0xae00000
	v_add_u32_e32 v130, s4, v181
	s_cselect_b32 s1, s1, 0xbe40000
	s_cselect_b32 s100, 0, 1
	s_waitcnt lgkmcnt(0)
	v_add_f32_e32 v128, v128, v129
	v_fmamk_f32 v128, v128, 0x3c800000, v186
	v_mul_f32_e32 v129, 0x4f800000, v128
	v_cmp_gt_f32_e32 vcc, s50, v128
	ds_read_b128 v[124:127], v130
	ds_read_b128 v[120:123], v130 offset:16
	ds_read_b128 v[116:119], v130 offset:128
	ds_read_b128 v[112:115], v130 offset:144
	v_cndmask_b32_e32 v128, v128, v129, vcc
	v_sqrt_f32_e32 v129, v128
	v_readlane_b32 s4, v237, 2
	v_readlane_b32 s5, v237, 3
	s_add_u32 s8, s4, s1
	v_add_u32_e32 v130, -1, v129
	v_fma_f32 v131, -v130, v129, v128
	s_addc_u32 s9, s5, 0
	s_mov_b32 s98, s8
	s_mov_b32 s99, s9
	v_cmp_ge_f32_e64 s[4:5], 0, v131
	v_add_u32_e32 v131, 1, v129
	s_lshl_b32 s0, s0, 9
	v_cndmask_b32_e64 v130, v129, v130, s[4:5]
	v_fma_f32 v129, -v131, v129, v128
	v_cmp_lt_f32_e64 s[4:5], 0, v129
	s_or_b32 s10, s0, s49
	v_pk_mul_f32 v[94:95], v[94:95], v[168:169] op_sel_hi:[1,0]
	v_cndmask_b32_e64 v129, v130, v131, s[4:5]
	v_mul_f32_e32 v130, 0x37800000, v129
	v_cndmask_b32_e32 v129, v129, v130, vcc
	v_cmp_class_f32_e32 vcc, v128, v187
	v_pk_mul_f32 v[92:93], v[92:93], v[168:169] op_sel_hi:[1,0]
	v_pk_mul_f32 v[84:85], v[84:85], v[168:169] op_sel_hi:[1,0]
	v_cndmask_b32_e32 v128, v129, v128, vcc
	v_div_scale_f32 v129, s[0:1], v128, v128, 1.0
	v_rcp_f32_e32 v170, v129
	s_add_u32 s0, s8, s10
	s_addc_u32 s1, s9, 0
	v_lshl_add_u64 v[130:131], s[0:1], 0, v[152:153]
	v_fma_f32 v189, -v129, v170, 1.0
	v_fmac_f32_e32 v170, v189, v170
	v_div_scale_f32 v189, vcc, 1.0, v128, 1.0
	v_mul_f32_e32 v194, v189, v170
	v_fma_f32 v195, -v129, v194, v189
	v_fmac_f32_e32 v194, v195, v170
	v_fma_f32 v129, -v129, v194, v189
	v_div_fmas_f32 v129, v129, v170, v194
	v_div_fixup_f32 v170, v129, v128, 1.0
	v_pk_mul_f32 v[142:143], v[142:143], v[170:171] op_sel_hi:[1,0]
	v_pk_mul_f32 v[172:173], v[172:173], v[170:171] op_sel_hi:[1,0]
	s_waitcnt lgkmcnt(0)
	v_pk_mul_f32 v[142:143], v[126:127], v[142:143]
	v_pk_mul_f32 v[190:191], v[190:191], v[170:171] op_sel_hi:[1,0]
	v_lshlrev_b64 v[128:129], 10, v[166:167]
	v_pk_mul_f32 v[172:173], v[124:125], v[172:173]
	v_pk_mul_f32 v[192:193], v[192:193], v[170:171] op_sel_hi:[1,0]
	v_pk_mul_f32 v[194:195], v[122:123], v[190:191]
	v_cvt_pk_bf16_f32 v190, v172, v173
	v_cvt_pk_bf16_f32 v191, v142, v143
	v_mov_b32_e32 v142, v171
	v_lshl_add_u64 v[128:129], v[130:131], 0, v[128:129]
	v_pk_mul_f32 v[192:193], v[120:121], v[192:193]
	v_pk_mul_f32 v[110:111], v[110:111], v[142:143] op_sel_hi:[1,0]
	v_pk_mul_f32 v[108:109], v[108:109], v[142:143] op_sel_hi:[1,0]
	v_cvt_pk_bf16_f32 v192, v192, v193
	v_cvt_pk_bf16_f32 v193, v194, v195
	v_accvgpr_write_b32 a0, v224
	v_accvgpr_write_b32 a1, v225
	v_accvgpr_write_b32 a2, v226
	v_accvgpr_write_b32 a3, v228
	v_accvgpr_write_b32 a4, v229
	v_subrev_u32_e32 v224, s98, v128
	v_lshrrev_b32_e32 v225, 10, v224
	v_and_b32_e32 v226, 0x3ff, v224
	v_lshrrev_b32_e32 v228, 7, v226
	v_mul_u32_u24_e32 v228, 0x204000, v228
	v_and_b32_e32 v226, 0x70, v226
	v_lshl_add_u32 v228, v226, 5, v228
	v_add_u32_e32 v229, 0x80, v225
	v_and_b32_e32 v226, 0xff, v225
	v_cmp_gt_u32_e32 vcc, 16, v226
	v_and_b32_e32 v224, 63, v226
	v_add_u32_e32 v226, 0x70, v226
	s_nop 1
	v_cndmask_b32_e32 v224, v224, v226, vcc
	v_cmp_lt_u32_e32 vcc, 0x3fff, v225
	s_nop 2
	v_cndmask_b32_e32 v229, v229, v224, vcc
	v_lshrrev_b32_e32 v224, 5, v229
; __device__ __forceinline__ unsigned cvt_pk_bf16(float lo, float hi) { unsigned r; asm volatile("v_cvt_pk_bf16_f32 %0, %1, %2" : "=v"(r) : "v"(lo), "v"(hi)); return r; }
;     __device__ __forceinline__ void operator()(const f32x4 (&acc)[2][2][4][2], const Unit& u, int wr, int wc, int fr, int fq) const {
;     ...
;                 for (int m = 0; m < 4; ++m) { const int row = row0 + ai * HALF + m * 16; const float rs = rsv[ai][m]; float sq = 0.f; f32x4 t[2][2];
; #pragma unroll
;                     for (int bj = 0; bj < 2; ++bj)
; #pragma unroll
;                         for (int n = 0; n < 2; ++n) { t[bj][n] = acc[ai][bj][m][n] * rs; sq += (t[bj][n][0] * t[bj][n][0] + t[bj][n][1] * t[bj][n][1]) + (t[bj][n][2] * t[bj][n][2] + t[bj][n][3] * t[bj][n][3]); }
;                     sq += __shfl_xor(sq, 16); sq += __shfl_xor(sq, 32);
;                     const float rn = 1.0f / sqrtf(sq * (1.0f / 64.0f) + 1e-6f);
; #pragma unroll
;                     for (int bj = 0; bj < 2; ++bj) { const f32x4 a = t[bj][0] * rn * gv[bj][0], b = t[bj][1] * rn * gv[bj][1];
;                         u32x4 w; w.x = cvt_pk_bf16(a[0], a[1]); w.y = cvt_pk_bf16(a[2], a[3]); w.z = cvt_pk_bf16(b[0], b[1]); w.w = cvt_pk_bf16(b[2], b[3]);
;                         *(u32x4*)(dst + (size_t)row * 512 + head * 64 + 32 * bj + 8 * fq) = w; } }
	v_lshl_add_u32 v228, v224, 12, v228
	v_and_b32_e32 v224, 31, v229
	v_lshl_add_u32 v228, v224, 4, v228
	v_mov_b32_e32 v229, 0
	v_lshl_add_u64 v[224:225], s[98:99], 0, v[228:229]
	v_cmp_eq_u32_e64 vcc, s100, 1
	s_nop 2
	v_cndmask_b32_e32 v224, v128, v224, vcc
	v_cndmask_b32_e32 v225, v129, v225, vcc
	global_store_dwordx4 v[224:225], v[190:193], off
	s_nop 1
	v_accvgpr_read_b32 v224, a0
	v_accvgpr_read_b32 v225, a1
	v_accvgpr_read_b32 v226, a2
	v_accvgpr_read_b32 v228, a3
	v_accvgpr_read_b32 v229, a4
	v_pk_mul_f32 v[172:173], v[110:111], v[110:111]
	v_pk_mul_f32 v[100:101], v[100:101], v[142:143] op_sel_hi:[1,0]
	v_pk_mul_f32 v[190:191], v[108:109], v[108:109]
	v_pk_mul_f32 v[102:103], v[102:103], v[142:143] op_sel_hi:[1,0]
	v_pk_mov_b32 v[192:193], v[190:191], v[172:173] op_sel:[1,0]
	v_mov_b32_e32 v191, v173
	v_pk_add_f32 v[172:173], v[192:193], v[190:191]
	v_pk_mul_f32 v[190:191], v[106:107], v[142:143] op_sel_hi:[1,0]
	v_pk_mul_f32 v[192:193], v[104:105], v[142:143] op_sel_hi:[1,0]
	v_pk_mul_f32 v[104:105], v[190:191], v[190:191]
	v_pk_mul_f32 v[106:107], v[192:193], v[192:193]
	v_pk_add_f32 v[172:173], v[172:173], v[172:173] op_sel_hi:[0,1]
	v_pk_mov_b32 v[194:195], v[106:107], v[104:105] op_sel:[1,0]
	v_mov_b32_e32 v107, v105
	v_pk_add_f32 v[104:105], v[194:195], v[106:107]
	v_pk_mul_f32 v[98:99], v[98:99], v[142:143] op_sel_hi:[1,0]
	v_pk_add_f32 v[104:105], v[104:105], v[104:105] op_sel_hi:[0,1]
	v_mul_f32_e32 v104, v100, v100
	v_pk_fma_f32 v[106:107], v[100:101], v[100:101], v[104:105] op_sel_hi:[1,1,0]
	v_mul_f32_e32 v104, v102, v102
	v_pk_fma_f32 v[194:195], v[102:103], v[102:103], v[104:105] op_sel_hi:[1,1,0]
	v_pk_mul_f32 v[96:97], v[96:97], v[142:143] op_sel_hi:[1,0]
	v_mul_f32_e32 v172, v98, v98
	v_mul_f32_e32 v106, v96, v96
	v_mul_f32_e32 v194, v97, v97
	v_mul_f32_e32 v104, v99, v99
	v_pk_add_f32 v[106:107], v[106:107], v[194:195]
	v_pk_add_f32 v[104:105], v[172:173], v[104:105]
	v_pk_mul_f32 v[134:135], v[134:135], v[170:171] op_sel_hi:[1,0]
	v_pk_add_f32 v[104:105], v[106:107], v[104:105]
	v_pk_mul_f32 v[106:107], v[136:137], v[170:171] op_sel_hi:[1,0]
	v_add_f32_e32 v142, v104, v105
	ds_bpermute_b32 v143, v140, v142
	v_pk_mul_f32 v[104:105], v[138:139], v[170:171] op_sel_hi:[1,0]
	v_pk_mul_f32 v[106:107], v[118:119], v[106:107]
	v_pk_mul_f32 v[104:105], v[116:117], v[104:105]
	v_pk_mul_f32 v[134:135], v[112:113], v[134:135]
	s_waitcnt lgkmcnt(0)
	v_add_f32_e32 v136, v142, v143
	ds_bpermute_b32 v137, v141, v136
	v_cvt_pk_bf16_f32 v104, v104, v105
	v_cvt_pk_bf16_f32 v105, v106, v107
	v_cvt_pk_bf16_f32 v106, v134, v135
	v_pk_mul_f32 v[132:133], v[132:133], v[170:171] op_sel_hi:[1,0]
	s_waitcnt lgkmcnt(0)
	v_add_f32_e32 v136, v136, v137
	v_fmamk_f32 v136, v136, 0x3c800000, v186
	v_mul_f32_e32 v137, 0x4f800000, v136
	v_cmp_gt_f32_e32 vcc, s50, v136
	v_pk_mul_f32 v[132:133], v[114:115], v[132:133]
	v_pk_mul_f32 v[86:87], v[86:87], v[168:169] op_sel_hi:[1,0]
	v_cndmask_b32_e32 v136, v136, v137, vcc
	v_sqrt_f32_e32 v137, v136
	v_pk_mul_f32 v[82:83], v[82:83], v[168:169] op_sel_hi:[1,0]
	v_pk_mul_f32 v[80:81], v[80:81], v[168:169] op_sel_hi:[1,0]
	v_pk_mul_f32 v[62:63], v[62:63], v[164:165] op_sel_hi:[1,0]
	v_add_u32_e32 v107, -1, v137
	v_fma_f32 v134, -v107, v137, v136
	v_cmp_ge_f32_e64 s[4:5], 0, v134
	v_add_u32_e32 v134, 1, v137
	v_fma_f32 v135, -v134, v137, v136
	v_cndmask_b32_e64 v107, v137, v107, s[4:5]
	v_cmp_lt_f32_e64 s[4:5], 0, v135
	v_pk_mul_f32 v[60:61], v[60:61], v[164:165] op_sel_hi:[1,0]
	v_pk_mul_f32 v[52:53], v[52:53], v[164:165] op_sel_hi:[1,0]
	v_cndmask_b32_e64 v107, v107, v134, s[4:5]
	v_mul_f32_e32 v134, 0x37800000, v107
	v_cndmask_b32_e32 v107, v107, v134, vcc
	v_cmp_class_f32_e32 vcc, v136, v187
	v_pk_mul_f32 v[54:55], v[54:55], v[164:165] op_sel_hi:[1,0]
	v_pk_mul_f32 v[50:51], v[50:51], v[164:165] op_sel_hi:[1,0]
	v_cndmask_b32_e32 v134, v107, v136, vcc
	v_div_scale_f32 v135, s[0:1], v134, v134, 1.0
	v_rcp_f32_e32 v136, v135
	v_cvt_pk_bf16_f32 v107, v132, v133
	v_accvgpr_write_b32 a0, v224
	v_accvgpr_write_b32 a1, v225
	v_accvgpr_write_b32 a2, v226
	v_accvgpr_write_b32 a3, v228
	v_accvgpr_write_b32 a4, v229
	v_subrev_u32_e32 v224, s98, v128
	v_add_u32_e32 v224, 64, v224
	v_lshrrev_b32_e32 v225, 10, v224
	v_and_b32_e32 v226, 0x3ff, v224
	v_lshrrev_b32_e32 v228, 7, v226
	v_mul_u32_u24_e32 v228, 0x204000, v228
	v_and_b32_e32 v226, 0x70, v226
	v_lshl_add_u32 v228, v226, 5, v228
	v_add_u32_e32 v229, 0x80, v225
	v_and_b32_e32 v226, 0xff, v225
	v_cmp_gt_u32_e32 vcc, 16, v226
	v_and_b32_e32 v224, 63, v226
	v_add_u32_e32 v226, 0x70, v226
	s_nop 1
	v_cndmask_b32_e32 v224, v224, v226, vcc
	v_cmp_lt_u32_e32 vcc, 0x3fff, v225
	s_nop 2
	v_cndmask_b32_e32 v229, v229, v224, vcc
	v_lshrrev_b32_e32 v224, 5, v229
	v_lshl_add_u32 v228, v224, 12, v228
	v_and_b32_e32 v224, 31, v229
	v_lshl_add_u32 v228, v224, 4, v228
	v_mov_b32_e32 v229, 0
	v_lshl_add_u64 v[224:225], s[98:99], 0, v[228:229]
	v_lshl_add_u64 v[228:229], v[128:129], 0, 64
	v_cmp_eq_u32_e64 vcc, s100, 1
	s_nop 2
	v_cndmask_b32_e32 v224, v228, v224, vcc
	v_cndmask_b32_e32 v225, v229, v225, vcc
	global_store_dwordx4 v[224:225], v[104:107], off
	s_nop 1
	v_accvgpr_read_b32 v224, a0
	v_accvgpr_read_b32 v225, a1
	v_accvgpr_read_b32 v226, a2
	v_accvgpr_read_b32 v228, a3
	v_accvgpr_read_b32 v229, a4
	v_pk_mul_f32 v[48:49], v[48:49], v[164:165] op_sel_hi:[1,0]
	v_pk_mul_f32 v[30:31], v[30:31], v[162:163] op_sel_hi:[1,0]
	v_fma_f32 v105, -v135, v136, 1.0
	v_fmac_f32_e32 v136, v105, v136
	v_div_scale_f32 v105, vcc, 1.0, v134, 1.0
	v_mul_f32_e32 v106, v105, v136
	v_fma_f32 v107, -v135, v106, v105
	v_fmac_f32_e32 v106, v107, v136
	v_fma_f32 v105, -v135, v106, v105
; __device__ __forceinline__ unsigned cvt_pk_bf16(float lo, float hi) { unsigned r; asm volatile("v_cvt_pk_bf16_f32 %0, %1, %2" : "=v"(r) : "v"(lo), "v"(hi)); return r; }
;     __device__ __forceinline__ void operator()(const f32x4 (&acc)[2][2][4][2], const Unit& u, int wr, int wc, int fr, int fq) const {
;     ...
;                 for (int m = 0; m < 4; ++m) { const int row = row0 + ai * HALF + m * 16; const float rs = rsv[ai][m]; float sq = 0.f; f32x4 t[2][2];
; #pragma unroll
;                     for (int bj = 0; bj < 2; ++bj)
; #pragma unroll
;                         for (int n = 0; n < 2; ++n) { t[bj][n] = acc[ai][bj][m][n] * rs; sq += (t[bj][n][0] * t[bj][n][0] + t[bj][n][1] * t[bj][n][1]) + (t[bj][n][2] * t[bj][n][2] + t[bj][n][3] * t[bj][n][3]); }
;                     sq += __shfl_xor(sq, 16); sq += __shfl_xor(sq, 32);
;                     const float rn = 1.0f / sqrtf(sq * (1.0f / 64.0f) + 1e-6f);
; #pragma unroll
;                     for (int bj = 0; bj < 2; ++bj) { const f32x4 a = t[bj][0] * rn * gv[bj][0], b = t[bj][1] * rn * gv[bj][1];
;                         u32x4 w; w.x = cvt_pk_bf16(a[0], a[1]); w.y = cvt_pk_bf16(a[2], a[3]); w.z = cvt_pk_bf16(b[0], b[1]); w.w = cvt_pk_bf16(b[2], b[3]);
;                         *(u32x4*)(dst + (size_t)row * 512 + head * 64 + 32 * bj + 8 * fq) = w; } }
	v_or_b32_e32 v104, 16, v166
	v_div_fmas_f32 v105, v105, v136, v106
	v_div_fixup_f32 v132, v105, v134, 1.0
	v_ashrrev_i32_e32 v105, 31, v104
	v_lshlrev_b64 v[104:105], 10, v[104:105]
	v_lshl_add_u64 v[134:135], v[130:131], 0, v[104:105]
	v_pk_mul_f32 v[104:105], v[108:109], v[132:133] op_sel_hi:[1,0]
	v_pk_mul_f32 v[106:107], v[110:111], v[132:133] op_sel_hi:[1,0]
	v_pk_mul_f32 v[104:105], v[124:125], v[104:105]
	v_pk_mul_f32 v[106:107], v[126:127], v[106:107]
	v_pk_mul_f32 v[108:109], v[192:193], v[132:133] op_sel_hi:[1,0]
	v_pk_mul_f32 v[110:111], v[190:191], v[132:133] op_sel_hi:[1,0]
	v_pk_mul_f32 v[108:109], v[120:121], v[108:109]
	v_pk_mul_f32 v[110:111], v[122:123], v[110:111]
	v_cvt_pk_bf16_f32 v104, v104, v105
	v_cvt_pk_bf16_f32 v105, v106, v107
	v_cvt_pk_bf16_f32 v106, v108, v109
	v_pk_mul_f32 v[96:97], v[96:97], v[132:133] op_sel_hi:[1,0]
	v_cvt_pk_bf16_f32 v107, v110, v111
	v_accvgpr_write_b32 a0, v224
	v_accvgpr_write_b32 a1, v225
	v_accvgpr_write_b32 a2, v226
	v_accvgpr_write_b32 a3, v228
	v_accvgpr_write_b32 a4, v229
	v_subrev_u32_e32 v224, s98, v134
	v_lshrrev_b32_e32 v225, 10, v224
	v_and_b32_e32 v226, 0x3ff, v224
	v_lshrrev_b32_e32 v228, 7, v226
	v_mul_u32_u24_e32 v228, 0x204000, v228
	v_and_b32_e32 v226, 0x70, v226
	v_lshl_add_u32 v228, v226, 5, v228
	v_add_u32_e32 v229, 0x80, v225
	v_and_b32_e32 v226, 0xff, v225
	v_cmp_gt_u32_e32 vcc, 16, v226
	v_and_b32_e32 v224, 63, v226
	v_add_u32_e32 v226, 0x70, v226
	s_nop 1
	v_cndmask_b32_e32 v224, v224, v226, vcc
	v_cmp_lt_u32_e32 vcc, 0x3fff, v225
	s_nop 2
	v_cndmask_b32_e32 v229, v229, v224, vcc
	v_lshrrev_b32_e32 v224, 5, v229
	v_lshl_add_u32 v228, v224, 12, v228
	v_and_b32_e32 v224, 31, v229
	v_lshl_add_u32 v228, v224, 4, v228
	v_mov_b32_e32 v229, 0
	v_lshl_add_u64 v[224:225], s[98:99], 0, v[228:229]
	v_cmp_eq_u32_e64 vcc, s100, 1
	s_nop 2
	v_cndmask_b32_e32 v224, v134, v224, vcc
	v_cndmask_b32_e32 v225, v135, v225, vcc
	global_store_dwordx4 v[224:225], v[104:107], off
	s_nop 1
	v_accvgpr_read_b32 v224, a0
	v_accvgpr_read_b32 v225, a1
	v_accvgpr_read_b32 v226, a2
	v_accvgpr_read_b32 v228, a3
	v_accvgpr_read_b32 v229, a4
	v_pk_mul_f32 v[96:97], v[112:113], v[96:97]
	v_pk_mul_f32 v[98:99], v[98:99], v[132:133] op_sel_hi:[1,0]
	v_pk_mul_f32 v[104:105], v[94:95], v[94:95]
	v_pk_mul_f32 v[106:107], v[92:93], v[92:93]
	v_pk_mul_f32 v[98:99], v[114:115], v[98:99]
	v_pk_mov_b32 v[108:109], v[106:107], v[104:105] op_sel:[1,0]
	v_mov_b32_e32 v107, v105
	v_pk_add_f32 v[104:105], v[108:109], v[106:107]
	v_pk_mul_f32 v[106:107], v[90:91], v[168:169] op_sel_hi:[1,0]
	v_pk_mul_f32 v[108:109], v[88:89], v[168:169] op_sel_hi:[1,0]
	v_pk_mul_f32 v[88:89], v[106:107], v[106:107]
	v_pk_mul_f32 v[90:91], v[108:109], v[108:109]
	v_pk_add_f32 v[104:105], v[104:105], v[104:105] op_sel_hi:[0,1]
	v_pk_mov_b32 v[110:111], v[90:91], v[88:89] op_sel:[1,0]
	v_mov_b32_e32 v91, v89
	v_pk_add_f32 v[88:89], v[110:111], v[90:91]
	v_mul_f32_e32 v104, v82, v82
	v_pk_add_f32 v[88:89], v[88:89], v[88:89] op_sel_hi:[0,1]
	v_mul_f32_e32 v88, v84, v84
	v_pk_fma_f32 v[90:91], v[84:85], v[84:85], v[88:89] op_sel_hi:[1,1,0]
	v_mul_f32_e32 v88, v86, v86
	v_pk_fma_f32 v[110:111], v[86:87], v[86:87], v[88:89] op_sel_hi:[1,1,0]
	v_mul_f32_e32 v90, v80, v80
	v_mul_f32_e32 v110, v81, v81
	v_mul_f32_e32 v88, v83, v83
	v_pk_add_f32 v[90:91], v[90:91], v[110:111]
	v_pk_add_f32 v[88:89], v[104:105], v[88:89]
	v_pk_mul_f32 v[28:29], v[28:29], v[162:163] op_sel_hi:[1,0]
	v_pk_add_f32 v[88:89], v[90:91], v[88:89]
	v_pk_mul_f32 v[90:91], v[102:103], v[132:133] op_sel_hi:[1,0]
	v_add_f32_e32 v104, v88, v89
	ds_bpermute_b32 v105, v140, v104
	v_pk_mul_f32 v[88:89], v[100:101], v[132:133] op_sel_hi:[1,0]
	v_pk_mul_f32 v[90:91], v[118:119], v[90:91]
	v_pk_mul_f32 v[88:89], v[116:117], v[88:89]
	v_pk_mul_f32 v[20:21], v[20:21], v[162:163] op_sel_hi:[1,0]
	s_waitcnt lgkmcnt(0)
	v_add_f32_e32 v100, v104, v105
	ds_bpermute_b32 v101, v141, v100
	v_cvt_pk_bf16_f32 v88, v88, v89
	v_cvt_pk_bf16_f32 v89, v90, v91
	v_cvt_pk_bf16_f32 v90, v96, v97
	v_pk_mul_f32 v[22:23], v[22:23], v[162:163] op_sel_hi:[1,0]
	s_waitcnt lgkmcnt(0)
	v_add_f32_e32 v100, v100, v101
	v_fmamk_f32 v100, v100, 0x3c800000, v186
	v_mul_f32_e32 v101, 0x4f800000, v100
	v_cmp_gt_f32_e32 vcc, s50, v100
	v_pk_mul_f32 v[18:19], v[18:19], v[162:163] op_sel_hi:[1,0]
	v_pk_mul_f32 v[16:17], v[16:17], v[162:163] op_sel_hi:[1,0]
	v_cndmask_b32_e32 v100, v100, v101, vcc
	v_sqrt_f32_e32 v101, v100
	s_nop 0
	v_add_u32_e32 v91, -1, v101
	v_fma_f32 v96, -v91, v101, v100
	v_cmp_ge_f32_e64 s[4:5], 0, v96
	v_add_u32_e32 v96, 1, v101
	v_fma_f32 v97, -v96, v101, v100
	v_cndmask_b32_e64 v91, v101, v91, s[4:5]
	v_cmp_lt_f32_e64 s[4:5], 0, v97
	s_nop 1
	v_cndmask_b32_e64 v91, v91, v96, s[4:5]
	v_mul_f32_e32 v96, 0x37800000, v91
	v_cndmask_b32_e32 v91, v91, v96, vcc
	v_cmp_class_f32_e32 vcc, v100, v187
	s_nop 1
	v_cndmask_b32_e32 v96, v91, v100, vcc
	v_div_scale_f32 v97, s[0:1], v96, v96, 1.0
	v_rcp_f32_e32 v100, v97
	v_cvt_pk_bf16_f32 v91, v98, v99
	v_accvgpr_write_b32 a0, v224
	v_accvgpr_write_b32 a1, v225
	v_accvgpr_write_b32 a2, v226
	v_accvgpr_write_b32 a3, v228
	v_accvgpr_write_b32 a4, v229
	v_subrev_u32_e32 v224, s98, v134
	v_add_u32_e32 v224, 64, v224
	v_lshrrev_b32_e32 v225, 10, v224
	v_and_b32_e32 v226, 0x3ff, v224
	v_lshrrev_b32_e32 v228, 7, v226
	v_mul_u32_u24_e32 v228, 0x204000, v228
	v_and_b32_e32 v226, 0x70, v226
	v_lshl_add_u32 v228, v226, 5, v228
	v_add_u32_e32 v229, 0x80, v225
	v_and_b32_e32 v226, 0xff, v225
	v_cmp_gt_u32_e32 vcc, 16, v226
	v_and_b32_e32 v224, 63, v226
	v_add_u32_e32 v226, 0x70, v226
	s_nop 1
	v_cndmask_b32_e32 v224, v224, v226, vcc
	v_cmp_lt_u32_e32 vcc, 0x3fff, v225
; __device__ __forceinline__ unsigned cvt_pk_bf16(float lo, float hi) { unsigned r; asm volatile("v_cvt_pk_bf16_f32 %0, %1, %2" : "=v"(r) : "v"(lo), "v"(hi)); return r; }
;     __device__ __forceinline__ void operator()(const f32x4 (&acc)[2][2][4][2], const Unit& u, int wr, int wc, int fr, int fq) const {
;     ...
;                 for (int m = 0; m < 4; ++m) { const int row = row0 + ai * HALF + m * 16; const float rs = rsv[ai][m]; float sq = 0.f; f32x4 t[2][2];
; #pragma unroll
;                     for (int bj = 0; bj < 2; ++bj)
; #pragma unroll
;                         for (int n = 0; n < 2; ++n) { t[bj][n] = acc[ai][bj][m][n] * rs; sq += (t[bj][n][0] * t[bj][n][0] + t[bj][n][1] * t[bj][n][1]) + (t[bj][n][2] * t[bj][n][2] + t[bj][n][3] * t[bj][n][3]); }
;                     sq += __shfl_xor(sq, 16); sq += __shfl_xor(sq, 32);
;                     const float rn = 1.0f / sqrtf(sq * (1.0f / 64.0f) + 1e-6f);
; #pragma unroll
;                     for (int bj = 0; bj < 2; ++bj) { const f32x4 a = t[bj][0] * rn * gv[bj][0], b = t[bj][1] * rn * gv[bj][1];
;                         u32x4 w; w.x = cvt_pk_bf16(a[0], a[1]); w.y = cvt_pk_bf16(a[2], a[3]); w.z = cvt_pk_bf16(b[0], b[1]); w.w = cvt_pk_bf16(b[2], b[3]);
;                         *(u32x4*)(dst + (size_t)row * 512 + head * 64 + 32 * bj + 8 * fq) = w; } }
	s_nop 2
	v_cndmask_b32_e32 v229, v229, v224, vcc
	v_lshrrev_b32_e32 v224, 5, v229
	v_lshl_add_u32 v228, v224, 12, v228
	v_and_b32_e32 v224, 31, v229
	v_lshl_add_u32 v228, v224, 4, v228
	v_mov_b32_e32 v229, 0
	v_lshl_add_u64 v[224:225], s[98:99], 0, v[228:229]
	v_lshl_add_u64 v[228:229], v[134:135], 0, 64
	v_cmp_eq_u32_e64 vcc, s100, 1
	s_nop 2
	v_cndmask_b32_e32 v224, v228, v224, vcc
	v_cndmask_b32_e32 v225, v229, v225, vcc
	global_store_dwordx4 v[224:225], v[88:91], off
	s_nop 1
	v_accvgpr_read_b32 v224, a0
	v_accvgpr_read_b32 v225, a1
	v_accvgpr_read_b32 v226, a2
	v_accvgpr_read_b32 v228, a3
	v_accvgpr_read_b32 v229, a4
	s_nop 1
	v_fma_f32 v89, -v97, v100, 1.0
	v_fmac_f32_e32 v100, v89, v100
	v_div_scale_f32 v89, vcc, 1.0, v96, 1.0
	v_mul_f32_e32 v90, v89, v100
	v_fma_f32 v91, -v97, v90, v89
	v_fmac_f32_e32 v90, v91, v100
	v_fma_f32 v89, -v97, v90, v89
	v_or_b32_e32 v88, 32, v166
	v_div_fmas_f32 v89, v89, v100, v90
	v_div_fixup_f32 v96, v89, v96, 1.0
	v_ashrrev_i32_e32 v89, 31, v88
	v_lshlrev_b64 v[88:89], 10, v[88:89]
	v_lshl_add_u64 v[98:99], v[130:131], 0, v[88:89]
	v_pk_mul_f32 v[88:89], v[92:93], v[96:97] op_sel_hi:[1,0]
	v_pk_mul_f32 v[90:91], v[94:95], v[96:97] op_sel_hi:[1,0]
	v_pk_mul_f32 v[88:89], v[124:125], v[88:89]
	v_pk_mul_f32 v[90:91], v[126:127], v[90:91]
	v_pk_mul_f32 v[92:93], v[108:109], v[96:97] op_sel_hi:[1,0]
	v_pk_mul_f32 v[94:95], v[106:107], v[96:97] op_sel_hi:[1,0]
	v_cvt_pk_bf16_f32 v88, v88, v89
	v_pk_mul_f32 v[92:93], v[120:121], v[92:93]
	v_pk_mul_f32 v[94:95], v[122:123], v[94:95]
	v_cvt_pk_bf16_f32 v89, v90, v91
	v_cvt_pk_bf16_f32 v90, v92, v93
	v_pk_mul_f32 v[80:81], v[80:81], v[96:97] op_sel_hi:[1,0]
	v_cvt_pk_bf16_f32 v91, v94, v95
	v_accvgpr_write_b32 a0, v224
	v_accvgpr_write_b32 a1, v225
	v_accvgpr_write_b32 a2, v226
	v_accvgpr_write_b32 a3, v228
	v_accvgpr_write_b32 a4, v229
	v_subrev_u32_e32 v224, s98, v98
	v_lshrrev_b32_e32 v225, 10, v224
	v_and_b32_e32 v226, 0x3ff, v224
	v_lshrrev_b32_e32 v228, 7, v226
	v_mul_u32_u24_e32 v228, 0x204000, v228
	v_and_b32_e32 v226, 0x70, v226
	v_lshl_add_u32 v228, v226, 5, v228
	v_add_u32_e32 v229, 0x80, v225
	v_and_b32_e32 v226, 0xff, v225
	v_cmp_gt_u32_e32 vcc, 16, v226
	v_and_b32_e32 v224, 63, v226
	v_add_u32_e32 v226, 0x70, v226
	s_nop 1
	v_cndmask_b32_e32 v224, v224, v226, vcc
	v_cmp_lt_u32_e32 vcc, 0x3fff, v225
	s_nop 2
	v_cndmask_b32_e32 v229, v229, v224, vcc
	v_lshrrev_b32_e32 v224, 5, v229
	v_lshl_add_u32 v228, v224, 12, v228
	v_and_b32_e32 v224, 31, v229
	v_lshl_add_u32 v228, v224, 4, v228
	v_mov_b32_e32 v229, 0
	v_lshl_add_u64 v[224:225], s[98:99], 0, v[228:229]
	v_cmp_eq_u32_e64 vcc, s100, 1
	s_nop 2
	v_cndmask_b32_e32 v224, v98, v224, vcc
	v_cndmask_b32_e32 v225, v99, v225, vcc
	global_store_dwordx4 v[224:225], v[88:91], off
	s_nop 1
	v_accvgpr_read_b32 v224, a0
	v_accvgpr_read_b32 v225, a1
	v_accvgpr_read_b32 v226, a2
	v_accvgpr_read_b32 v228, a3
	v_accvgpr_read_b32 v229, a4
	v_pk_mul_f32 v[80:81], v[112:113], v[80:81]
	v_pk_mul_f32 v[82:83], v[82:83], v[96:97] op_sel_hi:[1,0]
	v_mov_b32_e32 v88, v169
	v_pk_mul_f32 v[78:79], v[78:79], v[88:89] op_sel_hi:[1,0]
	v_pk_mul_f32 v[76:77], v[76:77], v[88:89] op_sel_hi:[1,0]
	v_pk_mul_f32 v[90:91], v[78:79], v[78:79]
	v_pk_mul_f32 v[92:93], v[76:77], v[76:77]
	v_pk_mul_f32 v[68:69], v[68:69], v[88:89] op_sel_hi:[1,0]
	v_pk_mov_b32 v[94:95], v[92:93], v[90:91] op_sel:[1,0]
	v_mov_b32_e32 v93, v91
	v_pk_add_f32 v[90:91], v[94:95], v[92:93]
	v_pk_mul_f32 v[92:93], v[74:75], v[88:89] op_sel_hi:[1,0]
	v_pk_mul_f32 v[94:95], v[72:73], v[88:89] op_sel_hi:[1,0]
	v_pk_mul_f32 v[72:73], v[92:93], v[92:93]
	v_pk_mul_f32 v[74:75], v[94:95], v[94:95]
	v_pk_mul_f32 v[70:71], v[70:71], v[88:89] op_sel_hi:[1,0]
	v_pk_mov_b32 v[100:101], v[74:75], v[72:73] op_sel:[1,0]
	v_mov_b32_e32 v75, v73
	v_pk_add_f32 v[72:73], v[100:101], v[74:75]
	v_pk_add_f32 v[90:91], v[90:91], v[90:91] op_sel_hi:[0,1]
	v_pk_add_f32 v[72:73], v[72:73], v[72:73] op_sel_hi:[0,1]
	v_mul_f32_e32 v72, v68, v68
	v_pk_fma_f32 v[74:75], v[68:69], v[68:69], v[72:73] op_sel_hi:[1,1,0]
	v_mul_f32_e32 v72, v70, v70
	v_pk_fma_f32 v[100:101], v[70:71], v[70:71], v[72:73] op_sel_hi:[1,1,0]
	v_pk_mul_f32 v[66:67], v[66:67], v[88:89] op_sel_hi:[1,0]
	v_pk_mul_f32 v[64:65], v[64:65], v[88:89] op_sel_hi:[1,0]
	v_mul_f32_e32 v90, v66, v66
	v_mul_f32_e32 v74, v64, v64
	v_mul_f32_e32 v100, v65, v65
	v_mul_f32_e32 v72, v67, v67
	v_pk_add_f32 v[74:75], v[74:75], v[100:101]
	v_pk_add_f32 v[72:73], v[90:91], v[72:73]
	v_pk_mul_f32 v[82:83], v[114:115], v[82:83]
	v_pk_add_f32 v[72:73], v[74:75], v[72:73]
	v_pk_mul_f32 v[74:75], v[86:87], v[96:97] op_sel_hi:[1,0]
	v_add_f32_e32 v88, v72, v73
	ds_bpermute_b32 v89, v140, v88
	v_pk_mul_f32 v[72:73], v[84:85], v[96:97] op_sel_hi:[1,0]
	v_pk_mul_f32 v[74:75], v[118:119], v[74:75]
	v_pk_mul_f32 v[72:73], v[116:117], v[72:73]
	s_waitcnt lgkmcnt(0)
	v_add_f32_e32 v84, v88, v89
	ds_bpermute_b32 v85, v141, v84
	v_cvt_pk_bf16_f32 v72, v72, v73
	v_cvt_pk_bf16_f32 v73, v74, v75
	v_cvt_pk_bf16_f32 v74, v80, v81
	s_waitcnt lgkmcnt(0)
; __device__ __forceinline__ unsigned cvt_pk_bf16(float lo, float hi) { unsigned r; asm volatile("v_cvt_pk_bf16_f32 %0, %1, %2" : "=v"(r) : "v"(lo), "v"(hi)); return r; }
;     __device__ __forceinline__ void operator()(const f32x4 (&acc)[2][2][4][2], const Unit& u, int wr, int wc, int fr, int fq) const {
;     ...
;                 for (int m = 0; m < 4; ++m) { const int row = row0 + ai * HALF + m * 16; const float rs = rsv[ai][m]; float sq = 0.f; f32x4 t[2][2];
; #pragma unroll
;                     for (int bj = 0; bj < 2; ++bj)
; #pragma unroll
;                         for (int n = 0; n < 2; ++n) { t[bj][n] = acc[ai][bj][m][n] * rs; sq += (t[bj][n][0] * t[bj][n][0] + t[bj][n][1] * t[bj][n][1]) + (t[bj][n][2] * t[bj][n][2] + t[bj][n][3] * t[bj][n][3]); }
;                     sq += __shfl_xor(sq, 16); sq += __shfl_xor(sq, 32);
;                     const float rn = 1.0f / sqrtf(sq * (1.0f / 64.0f) + 1e-6f);
; #pragma unroll
;                     for (int bj = 0; bj < 2; ++bj) { const f32x4 a = t[bj][0] * rn * gv[bj][0], b = t[bj][1] * rn * gv[bj][1];
;                         u32x4 w; w.x = cvt_pk_bf16(a[0], a[1]); w.y = cvt_pk_bf16(a[2], a[3]); w.z = cvt_pk_bf16(b[0], b[1]); w.w = cvt_pk_bf16(b[2], b[3]);
;                         *(u32x4*)(dst + (size_t)row * 512 + head * 64 + 32 * bj + 8 * fq) = w; } }
	v_add_f32_e32 v84, v84, v85
	v_fmamk_f32 v84, v84, 0x3c800000, v186
	v_mul_f32_e32 v85, 0x4f800000, v84
	v_cmp_gt_f32_e32 vcc, s50, v84
	s_nop 1
	v_cndmask_b32_e32 v84, v84, v85, vcc
	v_sqrt_f32_e32 v85, v84
	s_nop 0
	v_add_u32_e32 v75, -1, v85
	v_fma_f32 v80, -v75, v85, v84
	v_cmp_ge_f32_e64 s[4:5], 0, v80
	v_add_u32_e32 v80, 1, v85
	v_fma_f32 v81, -v80, v85, v84
	v_cndmask_b32_e64 v75, v85, v75, s[4:5]
	v_cmp_lt_f32_e64 s[4:5], 0, v81
	s_nop 1
	v_cndmask_b32_e64 v75, v75, v80, s[4:5]
	v_mul_f32_e32 v80, 0x37800000, v75
	v_cndmask_b32_e32 v75, v75, v80, vcc
	v_cmp_class_f32_e32 vcc, v84, v187
	s_nop 1
	v_cndmask_b32_e32 v80, v75, v84, vcc
	v_div_scale_f32 v81, s[0:1], v80, v80, 1.0
	v_rcp_f32_e32 v84, v81
	v_cvt_pk_bf16_f32 v75, v82, v83
	v_accvgpr_write_b32 a0, v224
	v_accvgpr_write_b32 a1, v225
	v_accvgpr_write_b32 a2, v226
	v_accvgpr_write_b32 a3, v228
	v_accvgpr_write_b32 a4, v229
	v_subrev_u32_e32 v224, s98, v98
	v_add_u32_e32 v224, 64, v224
	v_lshrrev_b32_e32 v225, 10, v224
	v_and_b32_e32 v226, 0x3ff, v224
	v_lshrrev_b32_e32 v228, 7, v226
	v_mul_u32_u24_e32 v228, 0x204000, v228
	v_and_b32_e32 v226, 0x70, v226
	v_lshl_add_u32 v228, v226, 5, v228
	v_add_u32_e32 v229, 0x80, v225
	v_and_b32_e32 v226, 0xff, v225
	v_cmp_gt_u32_e32 vcc, 16, v226
	v_and_b32_e32 v224, 63, v226
	v_add_u32_e32 v226, 0x70, v226
	s_nop 1
	v_cndmask_b32_e32 v224, v224, v226, vcc
	v_cmp_lt_u32_e32 vcc, 0x3fff, v225
	s_nop 2
	v_cndmask_b32_e32 v229, v229, v224, vcc
	v_lshrrev_b32_e32 v224, 5, v229
	v_lshl_add_u32 v228, v224, 12, v228
	v_and_b32_e32 v224, 31, v229
	v_lshl_add_u32 v228, v224, 4, v228
	v_mov_b32_e32 v229, 0
	v_lshl_add_u64 v[224:225], s[98:99], 0, v[228:229]
	v_lshl_add_u64 v[228:229], v[98:99], 0, 64
	v_cmp_eq_u32_e64 vcc, s100, 1
	s_nop 2
	v_cndmask_b32_e32 v224, v228, v224, vcc
	v_cndmask_b32_e32 v225, v229, v225, vcc
	global_store_dwordx4 v[224:225], v[72:75], off
	s_nop 1
	v_accvgpr_read_b32 v224, a0
	v_accvgpr_read_b32 v225, a1
	v_accvgpr_read_b32 v226, a2
	v_accvgpr_read_b32 v228, a3
	v_accvgpr_read_b32 v229, a4
	s_nop 1
	v_fma_f32 v73, -v81, v84, 1.0
	v_fmac_f32_e32 v84, v73, v84
	v_div_scale_f32 v73, vcc, 1.0, v80, 1.0
	v_mul_f32_e32 v74, v73, v84
	v_fma_f32 v75, -v81, v74, v73
	v_fmac_f32_e32 v74, v75, v84
	v_fma_f32 v73, -v81, v74, v73
	v_or_b32_e32 v72, 48, v166
	v_div_fmas_f32 v73, v73, v84, v74
	v_div_fixup_f32 v80, v73, v80, 1.0
	v_ashrrev_i32_e32 v73, 31, v72
	v_lshlrev_b64 v[72:73], 10, v[72:73]
	v_lshl_add_u64 v[82:83], v[130:131], 0, v[72:73]
	v_pk_mul_f32 v[72:73], v[76:77], v[80:81] op_sel_hi:[1,0]
	v_pk_mul_f32 v[74:75], v[78:79], v[80:81] op_sel_hi:[1,0]
	v_pk_mul_f32 v[76:77], v[94:95], v[80:81] op_sel_hi:[1,0]
	v_pk_mul_f32 v[78:79], v[92:93], v[80:81] op_sel_hi:[1,0]
	v_pk_mul_f32 v[74:75], v[126:127], v[74:75]
	v_pk_mul_f32 v[72:73], v[124:125], v[72:73]
	v_pk_mul_f32 v[78:79], v[122:123], v[78:79]
	v_pk_mul_f32 v[76:77], v[120:121], v[76:77]
	v_cvt_pk_bf16_f32 v72, v72, v73
	v_cvt_pk_bf16_f32 v73, v74, v75
	v_pk_mul_f32 v[64:65], v[64:65], v[80:81] op_sel_hi:[1,0]
	v_cvt_pk_bf16_f32 v74, v76, v77
	v_cvt_pk_bf16_f32 v75, v78, v79
	v_pk_mul_f32 v[76:77], v[62:63], v[62:63]
	v_pk_mul_f32 v[78:79], v[60:61], v[60:61]
	v_accvgpr_write_b32 a0, v224
	v_accvgpr_write_b32 a1, v225
	v_accvgpr_write_b32 a2, v226
	v_accvgpr_write_b32 a3, v228
	v_accvgpr_write_b32 a4, v229
	v_subrev_u32_e32 v224, s98, v82
	v_lshrrev_b32_e32 v225, 10, v224
	v_and_b32_e32 v226, 0x3ff, v224
	v_lshrrev_b32_e32 v228, 7, v226
	v_mul_u32_u24_e32 v228, 0x204000, v228
	v_and_b32_e32 v226, 0x70, v226
	v_lshl_add_u32 v228, v226, 5, v228
	v_add_u32_e32 v229, 0x80, v225
	v_and_b32_e32 v226, 0xff, v225
	v_cmp_gt_u32_e32 vcc, 16, v226
	v_and_b32_e32 v224, 63, v226
	v_add_u32_e32 v226, 0x70, v226
	s_nop 1
	v_cndmask_b32_e32 v224, v224, v226, vcc
	v_cmp_lt_u32_e32 vcc, 0x3fff, v225
	s_nop 2
	v_cndmask_b32_e32 v229, v229, v224, vcc
	v_lshrrev_b32_e32 v224, 5, v229
	v_lshl_add_u32 v228, v224, 12, v228
	v_and_b32_e32 v224, 31, v229
	v_lshl_add_u32 v228, v224, 4, v228
	v_mov_b32_e32 v229, 0
	v_lshl_add_u64 v[224:225], s[98:99], 0, v[228:229]
	v_cmp_eq_u32_e64 vcc, s100, 1
	s_nop 2
	v_cndmask_b32_e32 v224, v82, v224, vcc
	v_cndmask_b32_e32 v225, v83, v225, vcc
	global_store_dwordx4 v[224:225], v[72:75], off
	s_nop 1
	v_accvgpr_read_b32 v224, a0
	v_accvgpr_read_b32 v225, a1
	v_accvgpr_read_b32 v226, a2
	v_accvgpr_read_b32 v228, a3
	v_accvgpr_read_b32 v229, a4
	v_pk_mov_b32 v[84:85], v[78:79], v[76:77] op_sel:[1,0]
	v_mov_b32_e32 v79, v77
	v_pk_add_f32 v[76:77], v[84:85], v[78:79]
	v_pk_mul_f32 v[78:79], v[58:59], v[164:165] op_sel_hi:[1,0]
	v_pk_mul_f32 v[84:85], v[56:57], v[164:165] op_sel_hi:[1,0]
	v_pk_mul_f32 v[56:57], v[78:79], v[78:79]
	v_pk_mul_f32 v[58:59], v[84:85], v[84:85]
	v_pk_add_f32 v[76:77], v[76:77], v[76:77] op_sel_hi:[0,1]
	v_pk_mov_b32 v[86:87], v[58:59], v[56:57] op_sel:[1,0]
	v_mov_b32_e32 v59, v57
	v_pk_add_f32 v[56:57], v[86:87], v[58:59]
	v_mul_f32_e32 v76, v50, v50
	v_pk_add_f32 v[56:57], v[56:57], v[56:57] op_sel_hi:[0,1]
	v_mul_f32_e32 v56, v52, v52
	v_pk_fma_f32 v[58:59], v[52:53], v[52:53], v[56:57] op_sel_hi:[1,1,0]
	v_mul_f32_e32 v56, v54, v54
	v_pk_fma_f32 v[86:87], v[54:55], v[54:55], v[56:57] op_sel_hi:[1,1,0]
	v_mul_f32_e32 v58, v48, v48
	v_mul_f32_e32 v86, v49, v49
	v_mul_f32_e32 v56, v51, v51
	v_pk_add_f32 v[58:59], v[58:59], v[86:87]
	v_pk_add_f32 v[56:57], v[76:77], v[56:57]
	v_pk_mul_f32 v[66:67], v[66:67], v[80:81] op_sel_hi:[1,0]
	v_pk_add_f32 v[56:57], v[58:59], v[56:57]
	v_pk_mul_f32 v[58:59], v[70:71], v[80:81] op_sel_hi:[1,0]
	v_add_f32_e32 v76, v56, v57
	ds_bpermute_b32 v77, v140, v76
	v_pk_mul_f32 v[56:57], v[68:69], v[80:81] op_sel_hi:[1,0]
	v_pk_mul_f32 v[58:59], v[118:119], v[58:59]
	v_pk_mul_f32 v[56:57], v[116:117], v[56:57]
	v_pk_mul_f32 v[66:67], v[114:115], v[66:67]
	s_waitcnt lgkmcnt(0)
; __device__ __forceinline__ unsigned cvt_pk_bf16(float lo, float hi) { unsigned r; asm volatile("v_cvt_pk_bf16_f32 %0, %1, %2" : "=v"(r) : "v"(lo), "v"(hi)); return r; }
;     __device__ __forceinline__ void operator()(const f32x4 (&acc)[2][2][4][2], const Unit& u, int wr, int wc, int fr, int fq) const {
;     ...
;                 for (int m = 0; m < 4; ++m) { const int row = row0 + ai * HALF + m * 16; const float rs = rsv[ai][m]; float sq = 0.f; f32x4 t[2][2];
; #pragma unroll
;                     for (int bj = 0; bj < 2; ++bj)
; #pragma unroll
;                         for (int n = 0; n < 2; ++n) { t[bj][n] = acc[ai][bj][m][n] * rs; sq += (t[bj][n][0] * t[bj][n][0] + t[bj][n][1] * t[bj][n][1]) + (t[bj][n][2] * t[bj][n][2] + t[bj][n][3] * t[bj][n][3]); }
;                     sq += __shfl_xor(sq, 16); sq += __shfl_xor(sq, 32);
;                     const float rn = 1.0f / sqrtf(sq * (1.0f / 64.0f) + 1e-6f);
; #pragma unroll
;                     for (int bj = 0; bj < 2; ++bj) { const f32x4 a = t[bj][0] * rn * gv[bj][0], b = t[bj][1] * rn * gv[bj][1];
;                         u32x4 w; w.x = cvt_pk_bf16(a[0], a[1]); w.y = cvt_pk_bf16(a[2], a[3]); w.z = cvt_pk_bf16(b[0], b[1]); w.w = cvt_pk_bf16(b[2], b[3]);
;                         *(u32x4*)(dst + (size_t)row * 512 + head * 64 + 32 * bj + 8 * fq) = w; } }
	v_add_f32_e32 v68, v76, v77
	ds_bpermute_b32 v69, v141, v68
	v_cvt_pk_bf16_f32 v56, v56, v57
	v_cvt_pk_bf16_f32 v57, v58, v59
	v_pk_mul_f32 v[64:65], v[112:113], v[64:65]
	s_waitcnt lgkmcnt(0)
	v_add_f32_e32 v68, v68, v69
	v_fmamk_f32 v68, v68, 0x3c800000, v186
	v_mul_f32_e32 v69, 0x4f800000, v68
	v_cmp_gt_f32_e32 vcc, s50, v68
	s_nop 1
	v_cndmask_b32_e32 v68, v68, v69, vcc
	v_sqrt_f32_e32 v69, v68
	s_nop 0
	v_add_u32_e32 v58, -1, v69
	v_fma_f32 v59, -v58, v69, v68
	v_cmp_ge_f32_e64 s[4:5], 0, v59
	v_add_u32_e32 v59, 1, v69
	s_nop 0
	v_cndmask_b32_e64 v58, v69, v58, s[4:5]
	v_fma_f32 v69, -v59, v69, v68
	v_cmp_lt_f32_e64 s[4:5], 0, v69
	s_nop 1
	v_cndmask_b32_e64 v58, v58, v59, s[4:5]
	v_mul_f32_e32 v59, 0x37800000, v58
	v_cndmask_b32_e32 v58, v58, v59, vcc
	v_cmp_class_f32_e32 vcc, v68, v187
	s_nop 1
	v_cndmask_b32_e32 v68, v58, v68, vcc
	v_div_scale_f32 v69, s[0:1], v68, v68, 1.0
	v_rcp_f32_e32 v70, v69
	v_cvt_pk_bf16_f32 v58, v64, v65
	v_cvt_pk_bf16_f32 v59, v66, v67
	v_accvgpr_write_b32 a0, v224
	v_accvgpr_write_b32 a1, v225
	v_accvgpr_write_b32 a2, v226
	v_accvgpr_write_b32 a3, v228
	v_accvgpr_write_b32 a4, v229
	v_subrev_u32_e32 v224, s98, v82
	v_add_u32_e32 v224, 64, v224
	v_lshrrev_b32_e32 v225, 10, v224
	v_and_b32_e32 v226, 0x3ff, v224
	v_lshrrev_b32_e32 v228, 7, v226
	v_mul_u32_u24_e32 v228, 0x204000, v228
	v_and_b32_e32 v226, 0x70, v226
	v_lshl_add_u32 v228, v226, 5, v228
	v_add_u32_e32 v229, 0x80, v225
	v_and_b32_e32 v226, 0xff, v225
	v_cmp_gt_u32_e32 vcc, 16, v226
	v_and_b32_e32 v224, 63, v226
	v_add_u32_e32 v226, 0x70, v226
	s_nop 1
	v_cndmask_b32_e32 v224, v224, v226, vcc
	v_cmp_lt_u32_e32 vcc, 0x3fff, v225
	s_nop 2
	v_cndmask_b32_e32 v229, v229, v224, vcc
	v_lshrrev_b32_e32 v224, 5, v229
	v_lshl_add_u32 v228, v224, 12, v228
	v_and_b32_e32 v224, 31, v229
	v_lshl_add_u32 v228, v224, 4, v228
	v_mov_b32_e32 v229, 0
	v_lshl_add_u64 v[224:225], s[98:99], 0, v[228:229]
	v_lshl_add_u64 v[228:229], v[82:83], 0, 64
	v_cmp_eq_u32_e64 vcc, s100, 1
	s_nop 2
	v_cndmask_b32_e32 v224, v228, v224, vcc
	v_cndmask_b32_e32 v225, v229, v225, vcc
	global_store_dwordx4 v[224:225], v[56:59], off
	s_nop 1
	v_accvgpr_read_b32 v224, a0
	v_accvgpr_read_b32 v225, a1
	v_accvgpr_read_b32 v226, a2
	v_accvgpr_read_b32 v228, a3
	v_accvgpr_read_b32 v229, a4
	s_mov_b64 s[0:1], 0x20000
	v_lshl_add_u64 v[66:67], v[128:129], 0, s[0:1]
	v_fma_f32 v56, -v69, v70, 1.0
	v_fmac_f32_e32 v70, v56, v70
	v_div_scale_f32 v56, vcc, 1.0, v68, 1.0
	v_mul_f32_e32 v57, v56, v70
	v_fma_f32 v58, -v69, v57, v56
	v_fmac_f32_e32 v57, v58, v70
	v_fma_f32 v56, -v69, v57, v56
	v_div_fmas_f32 v56, v56, v70, v57
	v_div_fixup_f32 v64, v56, v68, 1.0
	v_pk_mul_f32 v[56:57], v[60:61], v[64:65] op_sel_hi:[1,0]
	v_pk_mul_f32 v[58:59], v[62:63], v[64:65] op_sel_hi:[1,0]
	v_pk_mul_f32 v[62:63], v[78:79], v[64:65] op_sel_hi:[1,0]
	v_pk_mul_f32 v[58:59], v[126:127], v[58:59]
	v_pk_mul_f32 v[56:57], v[124:125], v[56:57]
	v_pk_mul_f32 v[60:61], v[84:85], v[64:65] op_sel_hi:[1,0]
	v_pk_mul_f32 v[62:63], v[122:123], v[62:63]
	v_pk_mul_f32 v[60:61], v[120:121], v[60:61]
	v_cvt_pk_bf16_f32 v56, v56, v57
	v_cvt_pk_bf16_f32 v57, v58, v59
	s_mov_b32 s0, 0x20000
	v_cvt_pk_bf16_f32 v58, v60, v61
	v_cvt_pk_bf16_f32 v59, v62, v63
	v_mov_b32_e32 v62, v165
	v_pk_mul_f32 v[46:47], v[46:47], v[62:63] op_sel_hi:[1,0]
	v_pk_mul_f32 v[44:45], v[44:45], v[62:63] op_sel_hi:[1,0]
	v_pk_mul_f32 v[68:69], v[46:47], v[46:47]
	v_pk_mul_f32 v[70:71], v[44:45], v[44:45]
	v_pk_mul_f32 v[36:37], v[36:37], v[62:63] op_sel_hi:[1,0]
	v_pk_mov_b32 v[72:73], v[70:71], v[68:69] op_sel:[1,0]
	v_mov_b32_e32 v71, v69
	v_pk_add_f32 v[68:69], v[72:73], v[70:71]
	v_pk_mul_f32 v[70:71], v[42:43], v[62:63] op_sel_hi:[1,0]
	v_pk_mul_f32 v[72:73], v[40:41], v[62:63] op_sel_hi:[1,0]
	v_pk_mul_f32 v[40:41], v[70:71], v[70:71]
	v_pk_mul_f32 v[42:43], v[72:73], v[72:73]
	v_pk_mul_f32 v[38:39], v[38:39], v[62:63] op_sel_hi:[1,0]
	v_pk_mov_b32 v[74:75], v[42:43], v[40:41] op_sel:[1,0]
	v_mov_b32_e32 v43, v41
	v_pk_add_f32 v[40:41], v[74:75], v[42:43]
	v_pk_add_f32 v[68:69], v[68:69], v[68:69] op_sel_hi:[0,1]
	v_pk_add_f32 v[40:41], v[40:41], v[40:41] op_sel_hi:[0,1]
	v_mul_f32_e32 v40, v36, v36
	v_pk_fma_f32 v[42:43], v[36:37], v[36:37], v[40:41] op_sel_hi:[1,1,0]
	v_mul_f32_e32 v40, v38, v38
	v_pk_fma_f32 v[74:75], v[38:39], v[38:39], v[40:41] op_sel_hi:[1,1,0]
	v_pk_mul_f32 v[34:35], v[34:35], v[62:63] op_sel_hi:[1,0]
	v_pk_mul_f32 v[32:33], v[32:33], v[62:63] op_sel_hi:[1,0]
	v_mul_f32_e32 v68, v34, v34
	v_mul_f32_e32 v42, v32, v32
	v_mul_f32_e32 v74, v33, v33
	v_mul_f32_e32 v40, v35, v35
	v_pk_add_f32 v[42:43], v[42:43], v[74:75]
	v_pk_add_f32 v[40:41], v[68:69], v[40:41]
	v_add_co_u32_e32 v60, vcc, s0, v128
	v_pk_add_f32 v[40:41], v[42:43], v[40:41]
	s_nop 0
	v_addc_co_u32_e32 v61, vcc, 0, v129, vcc
	v_add_f32_e32 v62, v40, v41
	ds_bpermute_b32 v63, v140, v62
	v_pk_mul_f32 v[40:41], v[52:53], v[64:65] op_sel_hi:[1,0]
	v_pk_mul_f32 v[42:43], v[54:55], v[64:65] op_sel_hi:[1,0]
	v_pk_mul_f32 v[40:41], v[116:117], v[40:41]
	v_pk_mul_f32 v[42:43], v[118:119], v[42:43]
	s_waitcnt lgkmcnt(0)
; __device__ __forceinline__ unsigned cvt_pk_bf16(float lo, float hi) { unsigned r; asm volatile("v_cvt_pk_bf16_f32 %0, %1, %2" : "=v"(r) : "v"(lo), "v"(hi)); return r; }
;     __device__ __forceinline__ void operator()(const f32x4 (&acc)[2][2][4][2], const Unit& u, int wr, int wc, int fr, int fq) const {
;     ...
;                 for (int m = 0; m < 4; ++m) { const int row = row0 + ai * HALF + m * 16; const float rs = rsv[ai][m]; float sq = 0.f; f32x4 t[2][2];
; #pragma unroll
;                     for (int bj = 0; bj < 2; ++bj)
; #pragma unroll
;                         for (int n = 0; n < 2; ++n) { t[bj][n] = acc[ai][bj][m][n] * rs; sq += (t[bj][n][0] * t[bj][n][0] + t[bj][n][1] * t[bj][n][1]) + (t[bj][n][2] * t[bj][n][2] + t[bj][n][3] * t[bj][n][3]); }
;                     sq += __shfl_xor(sq, 16); sq += __shfl_xor(sq, 32);
;                     const float rn = 1.0f / sqrtf(sq * (1.0f / 64.0f) + 1e-6f);
; #pragma unroll
;                     for (int bj = 0; bj < 2; ++bj) { const f32x4 a = t[bj][0] * rn * gv[bj][0], b = t[bj][1] * rn * gv[bj][1];
;                         u32x4 w; w.x = cvt_pk_bf16(a[0], a[1]); w.y = cvt_pk_bf16(a[2], a[3]); w.z = cvt_pk_bf16(b[0], b[1]); w.w = cvt_pk_bf16(b[2], b[3]);
;                         *(u32x4*)(dst + (size_t)row * 512 + head * 64 + 32 * bj + 8 * fq) = w; } }
	v_add_f32_e32 v52, v62, v63
	ds_bpermute_b32 v53, v141, v52
	v_accvgpr_write_b32 a0, v224
	v_accvgpr_write_b32 a1, v225
	v_accvgpr_write_b32 a2, v226
	v_accvgpr_write_b32 a3, v228
	v_accvgpr_write_b32 a4, v229
	v_subrev_u32_e32 v224, s98, v60
	v_lshrrev_b32_e32 v225, 10, v224
	v_and_b32_e32 v226, 0x3ff, v224
	v_lshrrev_b32_e32 v228, 7, v226
	v_mul_u32_u24_e32 v228, 0x204000, v228
	v_and_b32_e32 v226, 0x70, v226
	v_lshl_add_u32 v228, v226, 5, v228
	v_add_u32_e32 v229, 0x80, v225
	v_and_b32_e32 v226, 0xff, v225
	v_cmp_gt_u32_e32 vcc, 16, v226
	v_and_b32_e32 v224, 63, v226
	v_add_u32_e32 v226, 0x70, v226
	s_nop 1
	v_cndmask_b32_e32 v224, v224, v226, vcc
	v_cmp_lt_u32_e32 vcc, 0x3fff, v225
	s_nop 2
	v_cndmask_b32_e32 v229, v229, v224, vcc
	v_lshrrev_b32_e32 v224, 5, v229
	v_lshl_add_u32 v228, v224, 12, v228
	v_and_b32_e32 v224, 31, v229
	v_lshl_add_u32 v228, v224, 4, v228
	v_mov_b32_e32 v229, 0
	v_lshl_add_u64 v[224:225], s[98:99], 0, v[228:229]
	v_cmp_eq_u32_e64 vcc, s100, 1
	s_nop 2
	v_cndmask_b32_e32 v224, v60, v224, vcc
	v_cndmask_b32_e32 v225, v61, v225, vcc
	global_store_dwordx4 v[224:225], v[56:59], off
	s_nop 1
	v_accvgpr_read_b32 v224, a0
	v_accvgpr_read_b32 v225, a1
	v_accvgpr_read_b32 v226, a2
	v_accvgpr_read_b32 v228, a3
	v_accvgpr_read_b32 v229, a4
	v_cvt_pk_bf16_f32 v40, v40, v41
	v_cvt_pk_bf16_f32 v41, v42, v43
	v_pk_mul_f32 v[48:49], v[48:49], v[64:65] op_sel_hi:[1,0]
	s_waitcnt lgkmcnt(0)
	v_add_f32_e32 v52, v52, v53
	v_fmamk_f32 v52, v52, 0x3c800000, v186
	v_mul_f32_e32 v53, 0x4f800000, v52
	v_cmp_gt_f32_e32 vcc, s50, v52
	v_pk_mul_f32 v[50:51], v[50:51], v[64:65] op_sel_hi:[1,0]
	v_pk_mul_f32 v[48:49], v[112:113], v[48:49]
	v_cndmask_b32_e32 v52, v52, v53, vcc
	v_sqrt_f32_e32 v53, v52
	v_pk_mul_f32 v[50:51], v[114:115], v[50:51]
	v_add_u32_e32 v42, -1, v53
	v_fma_f32 v43, -v42, v53, v52
	v_cmp_ge_f32_e64 s[4:5], 0, v43
	v_add_u32_e32 v43, 1, v53
	s_nop 0
	v_cndmask_b32_e64 v42, v53, v42, s[4:5]
	v_fma_f32 v53, -v43, v53, v52
	v_cmp_lt_f32_e64 s[4:5], 0, v53
	s_nop 1
	v_cndmask_b32_e64 v42, v42, v43, s[4:5]
	v_mul_f32_e32 v43, 0x37800000, v42
	v_cndmask_b32_e32 v42, v42, v43, vcc
	v_cmp_class_f32_e32 vcc, v52, v187
	s_nop 1
	v_cndmask_b32_e32 v52, v42, v52, vcc
	v_div_scale_f32 v53, s[0:1], v52, v52, 1.0
	v_rcp_f32_e32 v54, v53
	v_cvt_pk_bf16_f32 v42, v48, v49
	v_cvt_pk_bf16_f32 v43, v50, v51
	v_accvgpr_write_b32 a0, v224
	v_accvgpr_write_b32 a1, v225
	v_accvgpr_write_b32 a2, v226
	v_accvgpr_write_b32 a3, v228
	v_accvgpr_write_b32 a4, v229
	v_subrev_u32_e32 v224, s98, v66
	v_add_u32_e32 v224, 64, v224
	v_lshrrev_b32_e32 v225, 10, v224
	v_and_b32_e32 v226, 0x3ff, v224
	v_lshrrev_b32_e32 v228, 7, v226
	v_mul_u32_u24_e32 v228, 0x204000, v228
	v_and_b32_e32 v226, 0x70, v226
	v_lshl_add_u32 v228, v226, 5, v228
	v_add_u32_e32 v229, 0x80, v225
	v_and_b32_e32 v226, 0xff, v225
	v_cmp_gt_u32_e32 vcc, 16, v226
	v_and_b32_e32 v224, 63, v226
	v_add_u32_e32 v226, 0x70, v226
	s_nop 1
	v_cndmask_b32_e32 v224, v224, v226, vcc
	v_cmp_lt_u32_e32 vcc, 0x3fff, v225
	s_nop 2
	v_cndmask_b32_e32 v229, v229, v224, vcc
	v_lshrrev_b32_e32 v224, 5, v229
	v_lshl_add_u32 v228, v224, 12, v228
	v_and_b32_e32 v224, 31, v229
	v_lshl_add_u32 v228, v224, 4, v228
	v_mov_b32_e32 v229, 0
	v_lshl_add_u64 v[224:225], s[98:99], 0, v[228:229]
	v_lshl_add_u64 v[228:229], v[66:67], 0, 64
	v_cmp_eq_u32_e64 vcc, s100, 1
	s_nop 2
	v_cndmask_b32_e32 v224, v228, v224, vcc
	v_cndmask_b32_e32 v225, v229, v225, vcc
	global_store_dwordx4 v[224:225], v[40:43], off
	s_nop 1
	v_accvgpr_read_b32 v224, a0
	v_accvgpr_read_b32 v225, a1
	v_accvgpr_read_b32 v226, a2
	v_accvgpr_read_b32 v228, a3
	v_accvgpr_read_b32 v229, a4
	s_mov_b64 s[0:1], 0x24000
	v_lshl_add_u64 v[50:51], v[128:129], 0, s[0:1]
	v_fma_f32 v40, -v53, v54, 1.0
	v_fmac_f32_e32 v54, v40, v54
	v_div_scale_f32 v40, vcc, 1.0, v52, 1.0
	v_mul_f32_e32 v41, v40, v54
	v_fma_f32 v42, -v53, v41, v40
	v_fmac_f32_e32 v41, v42, v54
	v_fma_f32 v40, -v53, v41, v40
	v_div_fmas_f32 v40, v40, v54, v41
	v_div_fixup_f32 v48, v40, v52, 1.0
	v_pk_mul_f32 v[40:41], v[44:45], v[48:49] op_sel_hi:[1,0]
	v_pk_mul_f32 v[42:43], v[46:47], v[48:49] op_sel_hi:[1,0]
	v_pk_mul_f32 v[46:47], v[70:71], v[48:49] op_sel_hi:[1,0]
	v_pk_mul_f32 v[42:43], v[126:127], v[42:43]
	v_pk_mul_f32 v[40:41], v[124:125], v[40:41]
	v_pk_mul_f32 v[44:45], v[72:73], v[48:49] op_sel_hi:[1,0]
	v_pk_mul_f32 v[46:47], v[122:123], v[46:47]
	v_pk_mul_f32 v[44:45], v[120:121], v[44:45]
	v_cvt_pk_bf16_f32 v40, v40, v41
	v_cvt_pk_bf16_f32 v41, v42, v43
	v_pk_mul_f32 v[52:53], v[28:29], v[28:29]
	v_cvt_pk_bf16_f32 v42, v44, v45
	v_cvt_pk_bf16_f32 v43, v46, v47
	v_pk_mul_f32 v[46:47], v[30:31], v[30:31]
	s_mov_b32 s0, 0x24000
	v_pk_mov_b32 v[54:55], v[52:53], v[46:47] op_sel:[1,0]
	v_mov_b32_e32 v53, v47
	v_pk_add_f32 v[46:47], v[54:55], v[52:53]
	v_pk_mul_f32 v[52:53], v[26:27], v[162:163] op_sel_hi:[1,0]
	v_pk_mul_f32 v[54:55], v[24:25], v[162:163] op_sel_hi:[1,0]
	v_pk_mul_f32 v[24:25], v[52:53], v[52:53]
	v_pk_mul_f32 v[26:27], v[54:55], v[54:55]
	v_pk_add_f32 v[46:47], v[46:47], v[46:47] op_sel_hi:[0,1]
	v_pk_mov_b32 v[56:57], v[26:27], v[24:25] op_sel:[1,0]
	v_mov_b32_e32 v27, v25
	v_pk_add_f32 v[24:25], v[56:57], v[26:27]
	v_mul_f32_e32 v46, v18, v18
	v_pk_add_f32 v[24:25], v[24:25], v[24:25] op_sel_hi:[0,1]
	v_mul_f32_e32 v24, v20, v20
	v_pk_fma_f32 v[26:27], v[20:21], v[20:21], v[24:25] op_sel_hi:[1,1,0]
	v_mul_f32_e32 v24, v22, v22
	v_pk_fma_f32 v[56:57], v[22:23], v[22:23], v[24:25] op_sel_hi:[1,1,0]
	v_mul_f32_e32 v26, v16, v16
	v_mul_f32_e32 v56, v17, v17
	v_mul_f32_e32 v24, v19, v19
	v_pk_add_f32 v[26:27], v[26:27], v[56:57]
	v_pk_add_f32 v[24:25], v[46:47], v[24:25]
	v_add_co_u32_e32 v44, vcc, s0, v128
	v_pk_add_f32 v[24:25], v[26:27], v[24:25]
	s_nop 0
	v_addc_co_u32_e32 v45, vcc, 0, v129, vcc
	v_add_f32_e32 v46, v24, v25
	ds_bpermute_b32 v47, v140, v46
	v_pk_mul_f32 v[24:25], v[36:37], v[48:49] op_sel_hi:[1,0]
	v_pk_mul_f32 v[26:27], v[38:39], v[48:49] op_sel_hi:[1,0]
	v_pk_mul_f32 v[24:25], v[116:117], v[24:25]
	v_pk_mul_f32 v[26:27], v[118:119], v[26:27]
	s_waitcnt lgkmcnt(0)
; __device__ __forceinline__ unsigned cvt_pk_bf16(float lo, float hi) { unsigned r; asm volatile("v_cvt_pk_bf16_f32 %0, %1, %2" : "=v"(r) : "v"(lo), "v"(hi)); return r; }
;     __device__ __forceinline__ void operator()(const f32x4 (&acc)[2][2][4][2], const Unit& u, int wr, int wc, int fr, int fq) const {
;     ...
;                 for (int m = 0; m < 4; ++m) { const int row = row0 + ai * HALF + m * 16; const float rs = rsv[ai][m]; float sq = 0.f; f32x4 t[2][2];
; #pragma unroll
;                     for (int bj = 0; bj < 2; ++bj)
; #pragma unroll
;                         for (int n = 0; n < 2; ++n) { t[bj][n] = acc[ai][bj][m][n] * rs; sq += (t[bj][n][0] * t[bj][n][0] + t[bj][n][1] * t[bj][n][1]) + (t[bj][n][2] * t[bj][n][2] + t[bj][n][3] * t[bj][n][3]); }
;                     sq += __shfl_xor(sq, 16); sq += __shfl_xor(sq, 32);
;                     const float rn = 1.0f / sqrtf(sq * (1.0f / 64.0f) + 1e-6f);
; #pragma unroll
;                     for (int bj = 0; bj < 2; ++bj) { const f32x4 a = t[bj][0] * rn * gv[bj][0], b = t[bj][1] * rn * gv[bj][1];
;                         u32x4 w; w.x = cvt_pk_bf16(a[0], a[1]); w.y = cvt_pk_bf16(a[2], a[3]); w.z = cvt_pk_bf16(b[0], b[1]); w.w = cvt_pk_bf16(b[2], b[3]);
;                         *(u32x4*)(dst + (size_t)row * 512 + head * 64 + 32 * bj + 8 * fq) = w; } }
	v_add_f32_e32 v36, v46, v47
	ds_bpermute_b32 v37, v141, v36
	v_accvgpr_write_b32 a0, v224
	v_accvgpr_write_b32 a1, v225
	v_accvgpr_write_b32 a2, v226
	v_accvgpr_write_b32 a3, v228
	v_accvgpr_write_b32 a4, v229
	v_subrev_u32_e32 v224, s98, v44
	v_lshrrev_b32_e32 v225, 10, v224
	v_and_b32_e32 v226, 0x3ff, v224
	v_lshrrev_b32_e32 v228, 7, v226
	v_mul_u32_u24_e32 v228, 0x204000, v228
	v_and_b32_e32 v226, 0x70, v226
	v_lshl_add_u32 v228, v226, 5, v228
	v_add_u32_e32 v229, 0x80, v225
	v_and_b32_e32 v226, 0xff, v225
	v_cmp_gt_u32_e32 vcc, 16, v226
	v_and_b32_e32 v224, 63, v226
	v_add_u32_e32 v226, 0x70, v226
	s_nop 1
	v_cndmask_b32_e32 v224, v224, v226, vcc
	v_cmp_lt_u32_e32 vcc, 0x3fff, v225
	s_nop 2
	v_cndmask_b32_e32 v229, v229, v224, vcc
	v_lshrrev_b32_e32 v224, 5, v229
	v_lshl_add_u32 v228, v224, 12, v228
	v_and_b32_e32 v224, 31, v229
	v_lshl_add_u32 v228, v224, 4, v228
	v_mov_b32_e32 v229, 0
	v_lshl_add_u64 v[224:225], s[98:99], 0, v[228:229]
	v_cmp_eq_u32_e64 vcc, s100, 1
	s_nop 2
	v_cndmask_b32_e32 v224, v44, v224, vcc
	v_cndmask_b32_e32 v225, v45, v225, vcc
	global_store_dwordx4 v[224:225], v[40:43], off
	s_nop 1
	v_accvgpr_read_b32 v224, a0
	v_accvgpr_read_b32 v225, a1
	v_accvgpr_read_b32 v226, a2
	v_accvgpr_read_b32 v228, a3
	v_accvgpr_read_b32 v229, a4
	v_cvt_pk_bf16_f32 v24, v24, v25
	v_cvt_pk_bf16_f32 v25, v26, v27
	v_pk_mul_f32 v[32:33], v[32:33], v[48:49] op_sel_hi:[1,0]
	s_waitcnt lgkmcnt(0)
	v_add_f32_e32 v36, v36, v37
	v_fmamk_f32 v36, v36, 0x3c800000, v186
	v_mul_f32_e32 v37, 0x4f800000, v36
	v_cmp_gt_f32_e32 vcc, s50, v36
	v_pk_mul_f32 v[34:35], v[34:35], v[48:49] op_sel_hi:[1,0]
	v_pk_mul_f32 v[32:33], v[112:113], v[32:33]
	v_cndmask_b32_e32 v36, v36, v37, vcc
	v_sqrt_f32_e32 v37, v36
	v_pk_mul_f32 v[34:35], v[114:115], v[34:35]
	v_add_u32_e32 v26, -1, v37
	v_fma_f32 v27, -v26, v37, v36
	v_cmp_ge_f32_e64 s[4:5], 0, v27
	v_add_u32_e32 v27, 1, v37
	s_nop 0
	v_cndmask_b32_e64 v26, v37, v26, s[4:5]
	v_fma_f32 v37, -v27, v37, v36
	v_cmp_lt_f32_e64 s[4:5], 0, v37
	s_nop 1
	v_cndmask_b32_e64 v26, v26, v27, s[4:5]
	v_mul_f32_e32 v27, 0x37800000, v26
	v_cndmask_b32_e32 v26, v26, v27, vcc
	v_cmp_class_f32_e32 vcc, v36, v187
	s_nop 1
	v_cndmask_b32_e32 v36, v26, v36, vcc
	v_div_scale_f32 v37, s[0:1], v36, v36, 1.0
	v_rcp_f32_e32 v38, v37
	v_cvt_pk_bf16_f32 v26, v32, v33
	v_cvt_pk_bf16_f32 v27, v34, v35
	v_accvgpr_write_b32 a0, v224
	v_accvgpr_write_b32 a1, v225
	v_accvgpr_write_b32 a2, v226
	v_accvgpr_write_b32 a3, v228
	v_accvgpr_write_b32 a4, v229
	v_subrev_u32_e32 v224, s98, v50
	v_add_u32_e32 v224, 64, v224
	v_lshrrev_b32_e32 v225, 10, v224
	v_and_b32_e32 v226, 0x3ff, v224
	v_lshrrev_b32_e32 v228, 7, v226
	v_mul_u32_u24_e32 v228, 0x204000, v228
	v_and_b32_e32 v226, 0x70, v226
	v_lshl_add_u32 v228, v226, 5, v228
	v_add_u32_e32 v229, 0x80, v225
	v_and_b32_e32 v226, 0xff, v225
	v_cmp_gt_u32_e32 vcc, 16, v226
	v_and_b32_e32 v224, 63, v226
	v_add_u32_e32 v226, 0x70, v226
	s_nop 1
	v_cndmask_b32_e32 v224, v224, v226, vcc
	v_cmp_lt_u32_e32 vcc, 0x3fff, v225
	s_nop 2
	v_cndmask_b32_e32 v229, v229, v224, vcc
	v_lshrrev_b32_e32 v224, 5, v229
	v_lshl_add_u32 v228, v224, 12, v228
	v_and_b32_e32 v224, 31, v229
	v_lshl_add_u32 v228, v224, 4, v228
	v_mov_b32_e32 v229, 0
	v_lshl_add_u64 v[224:225], s[98:99], 0, v[228:229]
	v_lshl_add_u64 v[228:229], v[50:51], 0, 64
	v_cmp_eq_u32_e64 vcc, s100, 1
	s_nop 2
	v_cndmask_b32_e32 v224, v228, v224, vcc
	v_cndmask_b32_e32 v225, v229, v225, vcc
	global_store_dwordx4 v[224:225], v[24:27], off
	s_nop 1
	v_accvgpr_read_b32 v224, a0
	v_accvgpr_read_b32 v225, a1
	v_accvgpr_read_b32 v226, a2
	v_accvgpr_read_b32 v228, a3
	v_accvgpr_read_b32 v229, a4
	s_mov_b64 s[0:1], 0x28000
	v_lshl_add_u64 v[34:35], v[128:129], 0, s[0:1]
	v_fma_f32 v24, -v37, v38, 1.0
	v_fmac_f32_e32 v38, v24, v38
	v_div_scale_f32 v24, vcc, 1.0, v36, 1.0
	v_mul_f32_e32 v25, v24, v38
	v_fma_f32 v26, -v37, v25, v24
	v_fmac_f32_e32 v25, v26, v38
	v_fma_f32 v24, -v37, v25, v24
	v_div_fmas_f32 v24, v24, v38, v25
	v_div_fixup_f32 v32, v24, v36, 1.0
	v_pk_mul_f32 v[24:25], v[28:29], v[32:33] op_sel_hi:[1,0]
	v_pk_mul_f32 v[26:27], v[30:31], v[32:33] op_sel_hi:[1,0]
	v_pk_mul_f32 v[30:31], v[52:53], v[32:33] op_sel_hi:[1,0]
	v_pk_mul_f32 v[26:27], v[126:127], v[26:27]
	v_pk_mul_f32 v[24:25], v[124:125], v[24:25]
	v_pk_mul_f32 v[28:29], v[54:55], v[32:33] op_sel_hi:[1,0]
	v_pk_mul_f32 v[30:31], v[122:123], v[30:31]
	v_pk_mul_f32 v[28:29], v[120:121], v[28:29]
	v_cvt_pk_bf16_f32 v24, v24, v25
	v_cvt_pk_bf16_f32 v25, v26, v27
	s_mov_b32 s0, 0x28000
	v_cvt_pk_bf16_f32 v26, v28, v29
	v_cvt_pk_bf16_f32 v27, v30, v31
	v_mov_b32_e32 v30, v163
	v_pk_mul_f32 v[14:15], v[14:15], v[30:31] op_sel_hi:[1,0]
	v_pk_mul_f32 v[12:13], v[12:13], v[30:31] op_sel_hi:[1,0]
	v_pk_mul_f32 v[36:37], v[14:15], v[14:15]
	v_pk_mul_f32 v[38:39], v[12:13], v[12:13]
	v_pk_mul_f32 v[10:11], v[10:11], v[30:31] op_sel_hi:[1,0]
	v_pk_mov_b32 v[40:41], v[38:39], v[36:37] op_sel:[1,0]
	v_mov_b32_e32 v39, v37
	v_pk_add_f32 v[36:37], v[40:41], v[38:39]
	v_pk_mul_f32 v[8:9], v[8:9], v[30:31] op_sel_hi:[1,0]
	v_pk_add_f32 v[36:37], v[36:37], v[36:37] op_sel_hi:[0,1]
	v_pk_mul_f32 v[38:39], v[10:11], v[10:11]
	v_pk_mul_f32 v[40:41], v[8:9], v[8:9]
	v_pk_mul_f32 v[4:5], v[4:5], v[30:31] op_sel_hi:[1,0]
	v_pk_mov_b32 v[42:43], v[40:41], v[38:39] op_sel:[1,0]
	v_mov_b32_e32 v41, v39
	v_pk_mul_f32 v[6:7], v[6:7], v[30:31] op_sel_hi:[1,0]
	v_mul_f32_e32 v36, v4, v4
	v_pk_add_f32 v[38:39], v[42:43], v[40:41]
	v_pk_fma_f32 v[40:41], v[4:5], v[4:5], v[36:37] op_sel_hi:[1,1,0]
	v_mul_f32_e32 v36, v6, v6
	v_pk_add_f32 v[38:39], v[38:39], v[38:39] op_sel_hi:[0,1]
	v_pk_fma_f32 v[42:43], v[6:7], v[6:7], v[36:37] op_sel_hi:[1,1,0]
	v_pk_mul_f32 v[44:45], v[2:3], v[30:31] op_sel_hi:[1,0]
	v_pk_mul_f32 v[30:31], v[0:1], v[30:31] op_sel_hi:[1,0]
	v_mul_f32_e32 v36, v44, v44
	v_mul_f32_e32 v40, v30, v30
	v_mul_f32_e32 v42, v31, v31
	v_mul_f32_e32 v38, v45, v45
	v_pk_add_f32 v[0:1], v[40:41], v[42:43]
	v_pk_add_f32 v[2:3], v[36:37], v[38:39]
	v_add_co_u32_e32 v28, vcc, s0, v128
	v_pk_add_f32 v[0:1], v[0:1], v[2:3]
	s_nop 0
	v_addc_co_u32_e32 v29, vcc, 0, v129, vcc
	v_add_f32_e32 v33, v0, v1
	ds_bpermute_b32 v36, v140, v33
	v_pk_mul_f32 v[0:1], v[20:21], v[32:33] op_sel_hi:[1,0]
	v_pk_mul_f32 v[2:3], v[22:23], v[32:33] op_sel_hi:[1,0]
	v_pk_mul_f32 v[0:1], v[116:117], v[0:1]
	v_pk_mul_f32 v[2:3], v[118:119], v[2:3]
	s_waitcnt lgkmcnt(0)
; __device__ __forceinline__ unsigned cvt_pk_bf16(float lo, float hi) { unsigned r; asm volatile("v_cvt_pk_bf16_f32 %0, %1, %2" : "=v"(r) : "v"(lo), "v"(hi)); return r; }
;     __device__ __forceinline__ void operator()(const f32x4 (&acc)[2][2][4][2], const Unit& u, int wr, int wc, int fr, int fq) const {
;     ...
;                 for (int m = 0; m < 4; ++m) { const int row = row0 + ai * HALF + m * 16; const float rs = rsv[ai][m]; float sq = 0.f; f32x4 t[2][2];
; #pragma unroll
;                     for (int bj = 0; bj < 2; ++bj)
; #pragma unroll
;                         for (int n = 0; n < 2; ++n) { t[bj][n] = acc[ai][bj][m][n] * rs; sq += (t[bj][n][0] * t[bj][n][0] + t[bj][n][1] * t[bj][n][1]) + (t[bj][n][2] * t[bj][n][2] + t[bj][n][3] * t[bj][n][3]); }
;                     sq += __shfl_xor(sq, 16); sq += __shfl_xor(sq, 32);
;                     const float rn = 1.0f / sqrtf(sq * (1.0f / 64.0f) + 1e-6f);
; #pragma unroll
;                     for (int bj = 0; bj < 2; ++bj) { const f32x4 a = t[bj][0] * rn * gv[bj][0], b = t[bj][1] * rn * gv[bj][1];
;                         u32x4 w; w.x = cvt_pk_bf16(a[0], a[1]); w.y = cvt_pk_bf16(a[2], a[3]); w.z = cvt_pk_bf16(b[0], b[1]); w.w = cvt_pk_bf16(b[2], b[3]);
;                         *(u32x4*)(dst + (size_t)row * 512 + head * 64 + 32 * bj + 8 * fq) = w; } }
	v_add_f32_e32 v20, v33, v36
	ds_bpermute_b32 v21, v141, v20
	v_accvgpr_write_b32 a0, v224
	v_accvgpr_write_b32 a1, v225
	v_accvgpr_write_b32 a2, v226
	v_accvgpr_write_b32 a3, v228
	v_accvgpr_write_b32 a4, v229
	v_subrev_u32_e32 v224, s98, v28
	v_lshrrev_b32_e32 v225, 10, v224
	v_and_b32_e32 v226, 0x3ff, v224
	v_lshrrev_b32_e32 v228, 7, v226
	v_mul_u32_u24_e32 v228, 0x204000, v228
	v_and_b32_e32 v226, 0x70, v226
	v_lshl_add_u32 v228, v226, 5, v228
	v_add_u32_e32 v229, 0x80, v225
	v_and_b32_e32 v226, 0xff, v225
	v_cmp_gt_u32_e32 vcc, 16, v226
	v_and_b32_e32 v224, 63, v226
	v_add_u32_e32 v226, 0x70, v226
	s_nop 1
	v_cndmask_b32_e32 v224, v224, v226, vcc
	v_cmp_lt_u32_e32 vcc, 0x3fff, v225
	s_nop 2
	v_cndmask_b32_e32 v229, v229, v224, vcc
	v_lshrrev_b32_e32 v224, 5, v229
	v_lshl_add_u32 v228, v224, 12, v228
	v_and_b32_e32 v224, 31, v229
	v_lshl_add_u32 v228, v224, 4, v228
	v_mov_b32_e32 v229, 0
	v_lshl_add_u64 v[224:225], s[98:99], 0, v[228:229]
	v_cmp_eq_u32_e64 vcc, s100, 1
	s_nop 2
	v_cndmask_b32_e32 v224, v28, v224, vcc
	v_cndmask_b32_e32 v225, v29, v225, vcc
	global_store_dwordx4 v[224:225], v[24:27], off
	s_nop 1
	v_accvgpr_read_b32 v224, a0
	v_accvgpr_read_b32 v225, a1
	v_accvgpr_read_b32 v226, a2
	v_accvgpr_read_b32 v228, a3
	v_accvgpr_read_b32 v229, a4
	v_cvt_pk_bf16_f32 v0, v0, v1
	v_cvt_pk_bf16_f32 v1, v2, v3
	v_pk_mul_f32 v[16:17], v[16:17], v[32:33] op_sel_hi:[1,0]
	s_waitcnt lgkmcnt(0)
; __device__ __forceinline__ unsigned cvt_pk_bf16(float lo, float hi) { unsigned r; asm volatile("v_cvt_pk_bf16_f32 %0, %1, %2" : "=v"(r) : "v"(lo), "v"(hi)); return r; }
;     __device__ __forceinline__ void operator()(const f32x4 (&acc)[2][2][4][2], const Unit& u, int wr, int wc, int fr, int fq) const {
;     ...
;                 for (int m = 0; m < 4; ++m) { const int row = row0 + ai * HALF + m * 16; const float rs = rsv[ai][m]; float sq = 0.f; f32x4 t[2][2];
; #pragma unroll
;                     for (int bj = 0; bj < 2; ++bj)
; #pragma unroll
;                         for (int n = 0; n < 2; ++n) { t[bj][n] = acc[ai][bj][m][n] * rs; sq += (t[bj][n][0] * t[bj][n][0] + t[bj][n][1] * t[bj][n][1]) + (t[bj][n][2] * t[bj][n][2] + t[bj][n][3] * t[bj][n][3]); }
;                     sq += __shfl_xor(sq, 16); sq += __shfl_xor(sq, 32);
;                     const float rn = 1.0f / sqrtf(sq * (1.0f / 64.0f) + 1e-6f);
; #pragma unroll
;                     for (int bj = 0; bj < 2; ++bj) { const f32x4 a = t[bj][0] * rn * gv[bj][0], b = t[bj][1] * rn * gv[bj][1];
;                         u32x4 w; w.x = cvt_pk_bf16(a[0], a[1]); w.y = cvt_pk_bf16(a[2], a[3]); w.z = cvt_pk_bf16(b[0], b[1]); w.w = cvt_pk_bf16(b[2], b[3]);
;                         *(u32x4*)(dst + (size_t)row * 512 + head * 64 + 32 * bj + 8 * fq) = w; } }
	v_add_f32_e32 v20, v20, v21
	v_fmamk_f32 v20, v20, 0x3c800000, v186
	v_mul_f32_e32 v21, 0x4f800000, v20
	v_cmp_gt_f32_e32 vcc, s50, v20
	v_pk_mul_f32 v[18:19], v[18:19], v[32:33] op_sel_hi:[1,0]
	v_pk_mul_f32 v[16:17], v[112:113], v[16:17]
	v_cndmask_b32_e32 v20, v20, v21, vcc
	v_sqrt_f32_e32 v21, v20
	v_pk_mul_f32 v[18:19], v[114:115], v[18:19]
	v_add_u32_e32 v2, -1, v21
	v_fma_f32 v3, -v2, v21, v20
	v_cmp_ge_f32_e64 s[4:5], 0, v3
	v_add_u32_e32 v3, 1, v21
	s_nop 0
	v_cndmask_b32_e64 v2, v21, v2, s[4:5]
	v_fma_f32 v21, -v3, v21, v20
	v_cmp_lt_f32_e64 s[4:5], 0, v21
	s_nop 1
	v_cndmask_b32_e64 v2, v2, v3, s[4:5]
	v_mul_f32_e32 v3, 0x37800000, v2
	v_cndmask_b32_e32 v2, v2, v3, vcc
	v_cmp_class_f32_e32 vcc, v20, v187
	s_nop 1
	v_cndmask_b32_e32 v20, v2, v20, vcc
	v_div_scale_f32 v21, s[0:1], v20, v20, 1.0
	v_rcp_f32_e32 v22, v21
	v_cvt_pk_bf16_f32 v2, v16, v17
	v_cvt_pk_bf16_f32 v3, v18, v19
	v_accvgpr_write_b32 a0, v224
	v_accvgpr_write_b32 a1, v225
	v_accvgpr_write_b32 a2, v226
	v_accvgpr_write_b32 a3, v228
	v_accvgpr_write_b32 a4, v229
	v_subrev_u32_e32 v224, s98, v34
	v_add_u32_e32 v224, 64, v224
	v_lshrrev_b32_e32 v225, 10, v224
	v_and_b32_e32 v226, 0x3ff, v224
	v_lshrrev_b32_e32 v228, 7, v226
	v_mul_u32_u24_e32 v228, 0x204000, v228
	v_and_b32_e32 v226, 0x70, v226
	v_lshl_add_u32 v228, v226, 5, v228
	v_add_u32_e32 v229, 0x80, v225
	v_and_b32_e32 v226, 0xff, v225
	v_cmp_gt_u32_e32 vcc, 16, v226
	v_and_b32_e32 v224, 63, v226
	v_add_u32_e32 v226, 0x70, v226
	s_nop 1
	v_cndmask_b32_e32 v224, v224, v226, vcc
	v_cmp_lt_u32_e32 vcc, 0x3fff, v225
	s_nop 2
	v_cndmask_b32_e32 v229, v229, v224, vcc
	v_lshrrev_b32_e32 v224, 5, v229
	v_lshl_add_u32 v228, v224, 12, v228
	v_and_b32_e32 v224, 31, v229
	v_lshl_add_u32 v228, v224, 4, v228
	v_mov_b32_e32 v229, 0
	v_lshl_add_u64 v[224:225], s[98:99], 0, v[228:229]
	v_lshl_add_u64 v[228:229], v[34:35], 0, 64
	v_cmp_eq_u32_e64 vcc, s100, 1
	s_nop 2
	v_cndmask_b32_e32 v224, v228, v224, vcc
	v_cndmask_b32_e32 v225, v229, v225, vcc
	global_store_dwordx4 v[224:225], v[0:3], off
	s_nop 1
	v_accvgpr_read_b32 v224, a0
	v_accvgpr_read_b32 v225, a1
	v_accvgpr_read_b32 v226, a2
	v_accvgpr_read_b32 v228, a3
	v_accvgpr_read_b32 v229, a4
	v_lshl_add_u64 v[18:19], v[128:129], 0, s[18:19]
	s_nop 0
	v_fma_f32 v0, -v21, v22, 1.0
	v_fmac_f32_e32 v22, v0, v22
	v_div_scale_f32 v0, vcc, 1.0, v20, 1.0
	v_mul_f32_e32 v1, v0, v22
	v_fma_f32 v2, -v21, v1, v0
	v_fmac_f32_e32 v1, v2, v22
	v_fma_f32 v0, -v21, v1, v0
	v_div_fmas_f32 v0, v0, v22, v1
	v_div_fixup_f32 v16, v0, v20, 1.0
	v_pk_mul_f32 v[0:1], v[12:13], v[16:17] op_sel_hi:[1,0]
	v_pk_mul_f32 v[2:3], v[14:15], v[16:17] op_sel_hi:[1,0]
	v_pk_mul_f32 v[8:9], v[8:9], v[16:17] op_sel_hi:[1,0]
	v_pk_mul_f32 v[2:3], v[126:127], v[2:3]
	v_pk_mul_f32 v[0:1], v[124:125], v[0:1]
	v_pk_mul_f32 v[8:9], v[120:121], v[8:9]
	v_pk_mul_f32 v[10:11], v[10:11], v[16:17] op_sel_hi:[1,0]
	v_cvt_pk_bf16_f32 v0, v0, v1
	v_cvt_pk_bf16_f32 v1, v2, v3
	v_cvt_pk_bf16_f32 v2, v8, v9
	v_add_co_u32_e32 v8, vcc, s51, v128
	v_pk_mul_f32 v[10:11], v[122:123], v[10:11]
	s_nop 0
	v_addc_co_u32_e32 v9, vcc, 0, v129, vcc
	v_cvt_pk_bf16_f32 v3, v10, v11
	v_accvgpr_write_b32 a0, v224
	v_accvgpr_write_b32 a1, v225
	v_accvgpr_write_b32 a2, v226
	v_accvgpr_write_b32 a3, v228
	v_accvgpr_write_b32 a4, v229
	v_subrev_u32_e32 v224, s98, v8
	v_lshrrev_b32_e32 v225, 10, v224
	v_and_b32_e32 v226, 0x3ff, v224
	v_lshrrev_b32_e32 v228, 7, v226
	v_mul_u32_u24_e32 v228, 0x204000, v228
	v_and_b32_e32 v226, 0x70, v226
	v_lshl_add_u32 v228, v226, 5, v228
	v_add_u32_e32 v229, 0x80, v225
	v_and_b32_e32 v226, 0xff, v225
	v_cmp_gt_u32_e32 vcc, 16, v226
	v_and_b32_e32 v224, 63, v226
	v_add_u32_e32 v226, 0x70, v226
	s_nop 1
	v_cndmask_b32_e32 v224, v224, v226, vcc
	v_cmp_lt_u32_e32 vcc, 0x3fff, v225
	s_nop 2
	v_cndmask_b32_e32 v229, v229, v224, vcc
	v_lshrrev_b32_e32 v224, 5, v229
	v_lshl_add_u32 v228, v224, 12, v228
	v_and_b32_e32 v224, 31, v229
	v_lshl_add_u32 v228, v224, 4, v228
	v_mov_b32_e32 v229, 0
	v_lshl_add_u64 v[224:225], s[98:99], 0, v[228:229]
	v_cmp_eq_u32_e64 vcc, s100, 1
	s_nop 2
	v_cndmask_b32_e32 v224, v8, v224, vcc
	v_cndmask_b32_e32 v225, v9, v225, vcc
	global_store_dwordx4 v[224:225], v[0:3], off
	s_nop 1
	v_accvgpr_read_b32 v224, a0
	v_accvgpr_read_b32 v225, a1
	v_accvgpr_read_b32 v226, a2
	v_accvgpr_read_b32 v228, a3
	v_accvgpr_read_b32 v229, a4
	s_nop 1
	v_pk_mul_f32 v[0:1], v[4:5], v[16:17] op_sel_hi:[1,0]
	v_pk_mul_f32 v[2:3], v[6:7], v[16:17] op_sel_hi:[1,0]
	v_pk_mul_f32 v[0:1], v[116:117], v[0:1]
	v_pk_mul_f32 v[2:3], v[118:119], v[2:3]
	v_pk_mul_f32 v[4:5], v[30:31], v[16:17] op_sel_hi:[1,0]
	v_pk_mul_f32 v[6:7], v[44:45], v[16:17] op_sel_hi:[1,0]
	v_pk_mul_f32 v[4:5], v[112:113], v[4:5]
	v_pk_mul_f32 v[6:7], v[114:115], v[6:7]
	v_cvt_pk_bf16_f32 v0, v0, v1
	v_cvt_pk_bf16_f32 v1, v2, v3
	v_cvt_pk_bf16_f32 v2, v4, v5
	s_nop 0
	v_cvt_pk_bf16_f32 v3, v6, v7
	v_accvgpr_write_b32 a0, v224
	v_accvgpr_write_b32 a1, v225
	v_accvgpr_write_b32 a2, v226
	v_accvgpr_write_b32 a3, v228
	v_accvgpr_write_b32 a4, v229
	v_subrev_u32_e32 v224, s98, v18
	v_add_u32_e32 v224, 64, v224
	v_lshrrev_b32_e32 v225, 10, v224
	v_and_b32_e32 v226, 0x3ff, v224
	v_lshrrev_b32_e32 v228, 7, v226
	v_mul_u32_u24_e32 v228, 0x204000, v228
	v_and_b32_e32 v226, 0x70, v226
	v_lshl_add_u32 v228, v226, 5, v228
	v_add_u32_e32 v229, 0x80, v225
	v_and_b32_e32 v226, 0xff, v225
	v_cmp_gt_u32_e32 vcc, 16, v226
	v_and_b32_e32 v224, 63, v226
	v_add_u32_e32 v226, 0x70, v226
	s_nop 1
	v_cndmask_b32_e32 v224, v224, v226, vcc
	v_cmp_lt_u32_e32 vcc, 0x3fff, v225
	s_nop 2
	v_cndmask_b32_e32 v229, v229, v224, vcc
	v_lshrrev_b32_e32 v224, 5, v229
	v_lshl_add_u32 v228, v224, 12, v228
	v_and_b32_e32 v224, 31, v229
	v_lshl_add_u32 v228, v224, 4, v228
	v_mov_b32_e32 v229, 0
	v_lshl_add_u64 v[224:225], s[98:99], 0, v[228:229]
	v_lshl_add_u64 v[228:229], v[18:19], 0, 64
	v_cmp_eq_u32_e64 vcc, s100, 1
	s_nop 2
	v_cndmask_b32_e32 v224, v228, v224, vcc
	v_cndmask_b32_e32 v225, v229, v225, vcc
	global_store_dwordx4 v[224:225], v[0:3], off
	s_nop 1
	v_accvgpr_read_b32 v224, a0
	v_accvgpr_read_b32 v225, a1
	v_accvgpr_read_b32 v226, a2
	v_accvgpr_read_b32 v228, a3
	v_accvgpr_read_b32 v229, a4
	s_andn2_b64 vcc, exec, s[6:7]
	s_mov_b64 s[4:5], -1
	s_cbranch_vccnz .LBB0_761

; #define LAS __attribute__((address_space(3)))
; __device__ __forceinline__ void sb_load(SbTile& t, const bf16* SK, const bf16* SV, int h, int kt, int lane) {
;     const bf16* kp = SK + (size_t)pos2row(kt + (lane & 31)) * 512 + h * 64 + 8 * (lane >> 5);
;     const bf16* vp = SV + (size_t)pos2row(kt + (lane >> 1)) * 512 + h * 64 + 32 * (lane & 1);
; #pragma unroll
;     for (int j = 0; j < 4; ++j) { t.k[j] = *(const bf16x8*)(kp + 16 * j); t.v[j] = *(const u32x4*)(vp + 8 * j); }
; }
; __device__ __forceinline__ void sb_strip(const bf16* SQ, const bf16* SK, const bf16* SV, bf16* OMIX, int h, int qpos0, int lane, LAS unsigned char* vl) {
;     const int l32 = lane & 31, hi = lane >> 5;
;     const int qrow = qpos0 - 128 + l32;
;     SbTile t0, t1, t2;
;     sb_load(t0, SK, SV, h, qpos0, lane); sb_load(t1, SK, SV, h, qpos0 - 32, lane);
;     bf16x8 qf[4];
;     { const bf16* qp = SQ + (size_t)qrow * 512 + h * 64 + 8 * hi;
; #pragma unroll
;       for (int j = 0; j < 4; ++j) qf[j] = *(const bf16x8*)(qp + 16 * j); }
;     f32x16 o0, o1;
; #pragma unroll
;     for (int r = 0; r < 16; ++r) { o0[r] = 0.f; o1[r] = 0.f; }
;     float carry = 0.f;
;     const int qpos = qpos0 + l32;
;     LAS unsigned char* vw = vl + (lane >> 1) * 144 + (lane & 1) * 64;
;     const LAS unsigned char* vr = vl + (4 * hi + ((lane & 15) >> 2)) * 144 + (16 * ((lane >> 4) & 1) + 4 * (lane & 3)) * 2;
.LBB0_1043:
	s_lshl_b32 s4, s28, 5
	s_and_b32 s6, s4, 0x3fe0
	s_add_i32 s4, s6, 0x80
	v_or_b32_e32 v202, s4, v181
	v_add_u32_e32 v0, 0xffffff80, v202
	s_ashr_i32 s4, s28, 3
	v_lshlrev_b64 v[2:3], 10, v[0:1]
	s_and_b32 s24, s4, 0xffffffc0
	v_or_b32_e32 v0, s6, v193
	s_ashr_i32 s25, s24, 31
	v_lshlrev_b32_e32 v0, 10, v0
	v_lshl_add_u64 v[2:3], s[20:21], 0, v[2:3]
	s_lshl_b64 s[4:5], s[24:25], 1
	v_lshl_add_u64 v[4:5], s[22:23], 0, v[0:1]
	v_or_b32_e32 v192, s6, v181
	v_lshl_add_u64 v[2:3], v[2:3], 0, s[4:5]
	v_lshl_add_u64 v[4:5], v[4:5], 0, s[4:5]
	s_addk_i32 s6, 0x60
	s_mul_i32 s100, s24, 0x8100
	v_lshlrev_b32_e32 v222, 4, v201
	v_add_u32_e32 v222, s100, v222
	v_mov_b32_e32 v223, 0
	v_lshl_add_u64 v[218:219], s[20:21], 0, v[222:223]
	v_mov_b32_e32 v222, s6
	v_lshlrev_b32_e32 v222, 7, v222
	v_lshl_add_u64 v[226:227], v[218:219], 0, v[222:223]
	v_add_u32_e32 v222, 0x1000, v222
	v_lshl_add_u64 v[224:225], v[218:219], 0, v[222:223]
	s_and_b32 s46, s30, 0x3fe0
	v_lshl_add_u64 v[2:3], v[2:3], 0, v[186:187]
	v_lshl_add_u64 v[4:5], v[4:5], 0, v[188:189]
	v_or_b32_e32 v0, s6, v181
	global_load_dwordx4 v[118:121], v[4:5], off offset:48
	global_load_dwordx4 v[126:129], v[4:5], off offset:32
	global_load_dwordx4 v[130:133], v[4:5], off offset:16
	global_load_dwordx4 v[134:137], v[4:5], off
	global_load_dwordx4 v[90:93], v[224:225], off
	global_load_dwordx4 v[94:97], v[224:225], off offset:1024
	global_load_dwordx4 v[86:89], v[224:225], off offset:2048
	global_load_dwordx4 v[82:85], v[224:225], off offset:3072
	s_cmpk_gt_u32 s6, 0x7f
	v_add_u32_e32 v2, 0xffffff80, v0
	v_max_u32_e32 v0, 0x70, v0
	v_add_u32_e32 v0, 0x3f90, v0
	s_cselect_b64 vcc, -1, 0
	v_cndmask_b32_e32 v0, v0, v2, vcc
	v_lshlrev_b64 v[2:3], 10, v[0:1]
	v_or_b32_e32 v0, s6, v193
	v_add_u32_e32 v4, 0xffffff80, v0
	v_max_u32_e32 v0, 0x70, v0
	v_add_u32_e32 v0, 0x3f90, v0
	v_cndmask_b32_e32 v0, v0, v4, vcc
	v_lshlrev_b64 v[4:5], 10, v[0:1]
	v_lshl_add_u64 v[4:5], s[22:23], 0, v[4:5]
	v_lshl_add_u64 v[2:3], s[20:21], 0, v[2:3]
	v_lshl_add_u64 v[4:5], v[4:5], 0, s[4:5]
	v_lshl_add_u64 v[2:3], v[2:3], 0, s[4:5]
	v_lshl_add_u64 v[4:5], v[4:5], 0, v[188:189]
	v_readlane_b32 s6, v237, 35
	v_lshl_add_u64 v[2:3], v[2:3], 0, v[186:187]
	global_load_dwordx4 v[146:149], v[4:5], off offset:48
	global_load_dwordx4 v[150:153], v[4:5], off offset:32
	global_load_dwordx4 v[154:157], v[4:5], off offset:16
	global_load_dwordx4 v[158:161], v[4:5], off
	global_load_dwordx4 v[102:105], v[226:227], off
	global_load_dwordx4 v[110:113], v[226:227], off offset:1024
	global_load_dwordx4 v[106:109], v[226:227], off offset:2048
	global_load_dwordx4 v[98:101], v[226:227], off offset:3072
	v_lshlrev_b32_e32 v0, 10, v192
	v_readlane_b32 s7, v237, 36
	v_mov_b32_e32 v14, v1
	v_mov_b32_e32 v15, v1
	v_lshl_add_u64 v[2:3], s[6:7], 0, v[0:1]
	v_lshl_add_u64 v[2:3], v[2:3], 0, s[4:5]
	v_lshl_add_u64 v[2:3], v[2:3], 0, v[190:191]
	global_load_dwordx4 v[66:69], v[2:3], off
	global_load_dwordx4 v[70:73], v[2:3], off offset:32
	global_load_dwordx4 v[74:77], v[2:3], off offset:64
	global_load_dwordx4 v[78:81], v[2:3], off offset:96
	v_mov_b32_e32 v0, v1
	v_mov_b32_e32 v2, v1
	v_mov_b32_e32 v3, v1
	v_mov_b32_e32 v4, v1
	v_mov_b32_e32 v5, v1
	v_mov_b32_e32 v6, v1
	v_mov_b32_e32 v7, v1
	v_mov_b32_e32 v8, v1
	v_mov_b32_e32 v9, v1
	v_mov_b32_e32 v10, v1
	v_mov_b32_e32 v11, v1
	v_mov_b32_e32 v12, v1
	v_mov_b32_e32 v13, v1
	v_mov_b64_e32 v[32:33], v[14:15]
	v_mov_b64_e32 v[30:31], v[12:13]
	v_mov_b64_e32 v[28:29], v[10:11]
	v_mov_b64_e32 v[26:27], v[8:9]
	v_mov_b64_e32 v[24:25], v[6:7]
	v_mov_b64_e32 v[22:23], v[4:5]
	v_mov_b64_e32 v[20:21], v[2:3]
	v_mov_b64_e32 v[18:19], v[0:1]
	v_mov_b64_e32 v[16:17], v[14:15]
	v_or_b32_e32 v203, s46, v193
	v_or_b32_e32 v204, s46, v181
	v_or_b32_e32 v205, s46, v180
	v_lshl_add_u64 v[194:195], v[182:183], 0, s[4:5]
	v_lshl_add_u64 v[196:197], v[184:185], 0, s[4:5]
	s_mov_b32 s47, 0
	v_mov_b32_e32 v208, v1
	v_mov_b64_e32 v[14:15], v[12:13]
	v_mov_b64_e32 v[12:13], v[10:11]
	v_mov_b64_e32 v[10:11], v[8:9]
	v_mov_b64_e32 v[8:9], v[6:7]
	v_mov_b64_e32 v[6:7], v[4:5]
	v_mov_b64_e32 v[4:5], v[2:3]
	v_mov_b64_e32 v[2:3], v[0:1]
	s_branch .LBB0_1046

; #define SB_STEP(CUR, LD) { sb_load(LD, SK, SV, h, kt - 64, lane);     \
;         if (kt == qpos0 || kt < 128) sb_tile<true>(CUR, qf, o0, o1, carry, kt, qpos, hi, vw, vr); else sb_tile<false>(CUR, qf, o0, o1, carry, kt, qpos, hi, vw, vr); \
;         if (__all(carry > 152.0f)) break;     \
;         kt -= 32; if (kt < 96) break; }
; __device__ __forceinline__ void sb_load(SbTile& t, const bf16* SK, const bf16* SV, int h, int kt, int lane) {
;     const bf16* kp = SK + (size_t)pos2row(kt + (lane & 31)) * 512 + h * 64 + 8 * (lane >> 5);
;     const bf16* vp = SV + (size_t)pos2row(kt + (lane >> 1)) * 512 + h * 64 + 32 * (lane & 1);
; #pragma unroll
;     for (int j = 0; j < 4; ++j) { t.k[j] = *(const bf16x8*)(kp + 16 * j); t.v[j] = *(const u32x4*)(vp + 8 * j); }
; }
; __device__ __forceinline__ void sb_strip(const bf16* SQ, const bf16* SK, const bf16* SV, bf16* OMIX, int h, int qpos0, int lane, LAS unsigned char* vl) {
;     ...
;     for (int kt = qpos0;;) { SB_STEP(t0, t2) SB_STEP(t1, t0) SB_STEP(t2, t1) }
.LBB0_1046:
	s_add_i32 s49, s46, s47
	v_add_u32_e32 v206, s47, v204
	s_add_i32 s48, s49, 64
	v_add_u32_e32 v0, 64, v206
	s_cmpk_gt_u32 s48, 0x7f
	v_max_u32_e32 v0, 0x70, v0
	v_subrev_u32_e32 v34, 64, v206
	v_add_u32_e32 v0, 0x3f90, v0
	s_cselect_b64 vcc, -1, 0
	v_cndmask_b32_e32 v0, v0, v34, vcc
	v_add_u32_e32 v207, s47, v203
	v_lshlrev_b64 v[34:35], 10, v[0:1]
	v_add_u32_e32 v0, 64, v207
	v_max_u32_e32 v0, 0x70, v0
	v_subrev_u32_e32 v36, 64, v207
	v_add_u32_e32 v0, 0x3f90, v0
	v_cndmask_b32_e32 v0, v0, v36, vcc
	v_lshlrev_b64 v[36:37], 10, v[0:1]
	v_lshl_add_u64 v[36:37], v[196:197], 0, v[36:37]
	v_lshl_add_u64 v[34:35], v[194:195], 0, v[34:35]
	global_load_dwordx4 v[162:165], v[36:37], off offset:48
	global_load_dwordx4 v[166:169], v[36:37], off offset:32
	global_load_dwordx4 v[170:173], v[36:37], off offset:16
	global_load_dwordx4 v[174:177], v[36:37], off
	v_mov_b32_e32 v222, s48
	v_lshlrev_b32_e32 v222, 7, v222
	v_mov_b32_e32 v223, 0
	v_lshl_add_u64 v[220:221], v[218:219], 0, v[222:223]
	global_load_dwordx4 v[142:145], v[220:221], off
	global_load_dwordx4 v[138:141], v[220:221], off offset:1024
	global_load_dwordx4 v[122:125], v[220:221], off offset:2048
	global_load_dwordx4 v[114:117], v[220:221], off offset:3072
	v_add_co_u32_e64 v0, s[6:7], s49, v198
	s_nop 0
	v_readfirstlane_b32 s50, v0
	s_cmp_eq_u32 s47, 0
	v_exp_f32_e64 v0, -v208
	s_cselect_b64 s[4:5], -1, 0
	s_or_b64 s[4:5], s[4:5], s[6:7]
	s_andn2_b64 vcc, exec, s[4:5]
	s_mov_b64 s[4:5], -1
	s_waitcnt vmcnt(12)
	ds_write_b128 v199, v[134:137]
	ds_write_b128 v199, v[130:133] offset:16
	ds_write_b128 v199, v[126:129] offset:32
	ds_write_b128 v199, v[118:121] offset:48
	s_cbranch_vccz .LBB0_1048
; #define LAS __attribute__((address_space(3)))
; __device__ __forceinline__ unsigned cvtpk_s(float lo, float hi) { f32x2_t v = {lo, hi}; bf16x2_t b = __builtin_convertvector(v, bf16x2_t); return __builtin_bit_cast(unsigned, b); }
; template <bool MASK> __device__ __forceinline__ void sb_tile(const SbTile& t0, const bf16x8 (&qf)[4], f32x16& o0, f32x16& o1, float& carry, int kt, int qpos, int hi, LAS unsigned char* vw, const LAS unsigned char* vr) {
; #pragma unroll
;     for (int j = 0; j < 4; ++j) *(LAS u32x4*)(vw + 16 * j) = t0.v[j];
;     f32x16 z;
; #pragma unroll
;     for (int r = 0; r < 16; ++r) z[r] = 0.f;
; #pragma unroll
;     for (int j = 0; j < 4; ++j) z = MFMA32(t0.k[j], qf[j], z);
;     float kp[16], bt[16];
; #pragma unroll
;     for (int r = 0; r < 16; ++r) { const float e = __builtin_amdgcn_exp2f(z[r]); const float k = __builtin_amdgcn_rcpf(1.0f + e); const float b = e * k;
;         if (MASK) { const int kpos = kt + crow(r, hi); const bool okr = (kpos < qpos) && (kpos >= 112); kp[r] = okr ? k : 1.0f; bt[r] = okr ? b : 0.f; } else { kp[r] = k; bt[r] = b; } }
;     float G[4], Go[4];
; #pragma unroll
;     for (int g = 0; g < 4; ++g) { G[g] = (kp[4 * g] * kp[4 * g + 1]) * (kp[4 * g + 2] * kp[4 * g + 3]); Go[g] = __shfl_xor(G[g], 32); }
;     const float c0 = __builtin_amdgcn_exp2f(-carry);
;     float offs[4]; float T = 1.0f;
; #pragma unroll
;     for (int g = 3; g >= 0; --g) { offs[g] = c0 * T * (hi == 0 ? Go[g] : 1.0f); T *= G[g] * Go[g]; }
;     f32x16 w;
; #pragma unroll
;     for (int g = 0; g < 4; ++g) { float run = offs[g];
; #pragma unroll
;         for (int i = 3; i >= 0; --i) { const int r = 4 * g + i; w[r] = bt[r] * run; run *= kp[r]; } }
;     carry -= __builtin_amdgcn_logf(T);
; #pragma unroll
;     for (int s = 0; s < 2; ++s) { u32x4 wp;
; #pragma unroll
;         for (int i = 0; i < 4; ++i) wp[i] = cvtpk_s(w[8 * s + 2 * i], w[8 * s + 2 * i + 1]);
;         const bf16x8 wb = __builtin_bit_cast(bf16x8, wp);
;         const s16x4 a0 = vtr(vr + (16 * s) * 144), a1 = vtr(vr + (16 * s + 8) * 144), b0 = vtr(vr + (16 * s) * 144 + 64), b1 = vtr(vr + (16 * s + 8) * 144 + 64);
;         const bf16x8 v0 = __builtin_shufflevector(a0, a1, 0, 1, 2, 3, 4, 5, 6, 7), v1 = __builtin_shufflevector(b0, b1, 0, 1, 2, 3, 4, 5, 6, 7);
;         o0 = MFMA32(v0, wb, o0); o1 = MFMA32(v1, wb, o1); }
; }
	s_waitcnt vmcnt(11)
	v_mfma_f32_32x32x16_bf16 v[34:49], v[90:93], v[66:69], 0
	s_mov_b64 s[4:5], 0
	s_waitcnt vmcnt(10)
	v_mfma_f32_32x32x16_bf16 v[34:49], v[94:97], v[70:73], v[34:49]
	s_waitcnt vmcnt(9)
	v_mfma_f32_32x32x16_bf16 v[34:49], v[86:89], v[74:77], v[34:49]
	s_waitcnt vmcnt(8)
	v_mfma_f32_32x32x16_bf16 v[34:49], v[82:85], v[78:81], v[34:49]
	s_nop 11
	v_exp_f32_e32 v39, v39
	v_exp_f32_e32 v40, v40
	v_exp_f32_e32 v41, v41
	v_exp_f32_e32 v42, v42
	v_exp_f32_e32 v44, v44
	v_exp_f32_e32 v45, v45
	v_exp_f32_e32 v62, v46
	v_add_f32_e32 v55, 1.0, v39
	v_add_f32_e32 v57, 1.0, v40
	v_add_f32_e32 v58, 1.0, v41
	v_add_f32_e32 v59, 1.0, v42
	v_add_f32_e32 v61, 1.0, v44
	v_add_f32_e32 v46, 1.0, v45
	v_rcp_f32_e32 v56, v55
	v_rcp_f32_e32 v55, v57
	v_rcp_f32_e32 v57, v58
	v_rcp_f32_e32 v58, v59
	v_rcp_f32_e32 v59, v61
	v_rcp_f32_e32 v61, v46
	v_exp_f32_e32 v63, v47
	v_add_f32_e32 v46, 1.0, v62
	v_rcp_f32_e32 v64, v46
	v_exp_f32_e32 v46, v48
	v_exp_f32_e32 v47, v49
	v_exp_f32_e32 v43, v43
	v_add_f32_e32 v48, 1.0, v63
	v_exp_f32_e32 v38, v38
	v_rcp_f32_e32 v130, v48
	v_add_f32_e32 v48, 1.0, v46
	v_rcp_f32_e32 v65, v48
	v_add_f32_e32 v48, 1.0, v47
	v_add_f32_e32 v60, 1.0, v43
	v_rcp_f32_e32 v131, v48
	v_rcp_f32_e32 v60, v60
	v_add_f32_e32 v54, 1.0, v38
	v_and_b32_e32 v49, 64, v201
	v_exp_f32_e32 v36, v36
	v_exp_f32_e32 v37, v37
	v_rcp_f32_e32 v54, v54
	v_xor_b32_e32 v48, 32, v201
	v_add_u32_e32 v49, 64, v49
	v_exp_f32_e32 v34, v34
	v_exp_f32_e32 v35, v35
	v_cmp_lt_i32_e32 vcc, v48, v49
	v_pk_mul_f32 v[118:119], v[64:65], v[130:131]
	v_add_f32_e32 v52, 1.0, v36
	v_cndmask_b32_e32 v48, v201, v48, vcc
	v_mul_f32_e32 v120, v118, v119
	v_pk_mul_f32 v[118:119], v[58:59], v[60:61]
	v_lshlrev_b32_e32 v126, 2, v48
	v_mul_f32_e32 v118, v118, v119
	v_add_f32_e32 v53, 1.0, v37
	v_pk_mul_f32 v[48:49], v[54:55], v[56:57]
	ds_bpermute_b32 v121, v126, v120
	ds_bpermute_b32 v127, v126, v118
	v_add_f32_e32 v50, 1.0, v34
	v_add_f32_e32 v51, 1.0, v35
	v_rcp_f32_e32 v52, v52
	v_rcp_f32_e32 v53, v53
	v_pk_mul_f32 v[48:49], v[48:49], v[48:49] op_sel:[0,1] op_sel_hi:[1,0]
	v_rcp_f32_e32 v50, v50
	v_rcp_f32_e32 v51, v51
	ds_bpermute_b32 v49, v126, v48
	s_waitcnt lgkmcnt(2)
	v_cndmask_b32_e64 v128, 1.0, v121, s[0:1]
	v_mul_f32_e32 v119, v120, v121
	s_waitcnt lgkmcnt(1)
	v_mul_f32_e32 v121, v118, v127
	v_mov_b32_e32 v118, v52
	v_mov_b32_e32 v120, v53
	v_mul_f32_e32 v129, v0, v119
	v_pk_mul_f32 v[118:119], v[118:119], v[120:121]
	v_mov_b32_e32 v120, v50
	v_mov_b32_e32 v121, v48
	v_mov_b32_e32 v48, v51
	v_cndmask_b32_e64 v132, 1.0, v127, s[0:1]
	s_waitcnt lgkmcnt(0)
	v_cndmask_b32_e64 v127, 1.0, v49, s[0:1]
	v_pk_mul_f32 v[48:49], v[120:121], v[48:49]
	v_pk_mul_f32 v[36:37], v[36:37], v[52:53]
	v_pk_mul_f32 v[210:211], v[48:49], v[118:119]
	ds_bpermute_b32 v209, v126, v210
	v_mul_f32_e32 v48, v0, v211
	v_pk_mul_f32 v[34:35], v[34:35], v[50:51]
	v_mul_f32_e32 v118, v0, v119
	v_mov_b32_e32 v50, v54
	s_waitcnt lgkmcnt(0)
	v_cndmask_b32_e64 v49, 1.0, v209, s[0:1]
	v_mul_f32_e32 v49, v49, v48
	v_mul_f32_e32 v48, v53, v49
	v_pk_mul_f32 v[36:37], v[36:37], v[48:49]
	v_mul_f32_e32 v49, v52, v48
	v_mul_f32_e32 v48, v51, v49
	v_pk_mul_f32 v[34:35], v[34:35], v[48:49]
	v_mov_b32_e32 v48, v55
	v_mov_b32_e32 v49, v57
	v_pk_mul_f32 v[40:41], v[40:41], v[48:49]
	v_mul_f32_e32 v49, v127, v118
	v_mul_f32_e32 v48, v57, v49
	v_pk_mul_f32 v[40:41], v[40:41], v[48:49]
	v_mov_b32_e32 v51, v56
	v_mul_f32_e32 v49, v55, v48
	v_pk_mul_f32 v[38:39], v[38:39], v[50:51]
	v_mul_f32_e32 v48, v56, v49
	v_pk_mul_f32 v[38:39], v[38:39], v[48:49]
	v_mov_b32_e32 v48, v59
	v_mov_b32_e32 v49, v61
	v_pk_mul_f32 v[44:45], v[44:45], v[48:49]
	v_mul_f32_e32 v49, v132, v129
	v_mul_f32_e32 v48, v61, v49
	v_pk_mul_f32 v[134:135], v[44:45], v[48:49]
	v_mov_b32_e32 v44, v58
	v_mov_b32_e32 v45, v60
	ds_read_b64_tr_b16 v[50:51], v200
	ds_read_b64_tr_b16 v[52:53], v200 offset:1152
	v_pk_mul_f32 v[42:43], v[42:43], v[44:45]
	v_mul_f32_e32 v45, v59, v48
	v_mul_f32_e32 v55, v0, v128
	ds_read_b64_tr_b16 v[128:129], v200 offset:1216
	ds_read_b64_tr_b16 v[126:127], v200 offset:64
	v_mul_f32_e32 v44, v60, v45
	v_pk_mul_f32 v[136:137], v[42:43], v[44:45]
	v_mov_b32_e32 v42, v65
	v_mov_b32_e32 v43, v131
	v_pk_mul_f32 v[42:43], v[46:47], v[42:43]
	v_mul_f32_e32 v54, v131, v55
	v_cvt_pk_bf16_f32 v118, v34, v35
	v_cvt_pk_bf16_f32 v119, v36, v37
	v_cvt_pk_bf16_f32 v120, v38, v39
	v_cvt_pk_bf16_f32 v121, v40, v41
	v_pk_mul_f32 v[212:213], v[42:43], v[54:55]
	v_mul_f32_e32 v217, v65, v54
	s_waitcnt lgkmcnt(2)
	v_mfma_f32_32x32x16_bf16 v[34:49], v[50:53], v[118:121], v[2:17]
	v_mov_b32_e32 v50, v64
	v_mov_b32_e32 v51, v130
	v_mul_f32_e64 v214, v62, v50
	v_mul_f32_e64 v215, v63, v51
	v_mul_f32_e32 v216, v130, v217
	ds_read_b64_tr_b16 v[130:131], v200 offset:2304
	ds_read_b64_tr_b16 v[132:133], v200 offset:3456
	s_waitcnt lgkmcnt(2)
	v_mfma_f32_32x32x16_bf16 v[50:65], v[126:129], v[118:121], v[18:33]
	v_cvt_pk_bf16_f32 v126, v136, v137
	v_cvt_pk_bf16_f32 v127, v134, v135
	ds_read_b64_tr_b16 v[136:137], v200 offset:3520
	ds_read_b64_tr_b16 v[134:135], v200 offset:2368
	v_mul_f32_e64 v118, v214, v216
	v_mul_f32_e64 v119, v215, v217
	v_cvt_pk_bf16_f32 v129, v212, v213
	v_cvt_pk_bf16_f32 v128, v118, v119
	v_mul_f32_e32 v118, v210, v209
	v_mul_f32_e32 v118, v118, v211
	s_waitcnt lgkmcnt(2)
	v_mfma_f32_32x32x16_bf16 v[34:49], v[130:133], v[126:129], v[34:49]
	v_log_f32_e32 v118, v118
	s_waitcnt lgkmcnt(0)
	v_mfma_f32_32x32x16_bf16 v[50:65], v[134:137], v[126:129], v[50:65]

; __device__ __forceinline__ void sb_load(SbTile& t, const bf16* SK, const bf16* SV, int h, int kt, int lane) {
;     const bf16* kp = SK + (size_t)pos2row(kt + (lane & 31)) * 512 + h * 64 + 8 * (lane >> 5);
;     const bf16* vp = SV + (size_t)pos2row(kt + (lane >> 1)) * 512 + h * 64 + 32 * (lane & 1);
; #pragma unroll
;     for (int j = 0; j < 4; ++j) { t.k[j] = *(const bf16x8*)(kp + 16 * j); t.v[j] = *(const u32x4*)(vp + 8 * j); }
; }
.LBB0_1050:
	v_sub_f32_e32 v208, v208, v118
	v_cmp_lt_f32_e32 vcc, s45, v208
	s_cmp_eq_u64 vcc, exec
	s_cselect_b64 s[4:5], -1, 0
	s_or_b64 s[6:7], s[4:5], s[6:7]
	s_mov_b64 s[4:5], -1
	s_and_b64 vcc, exec, s[6:7]
	s_cbranch_vccnz .LBB0_1044
	s_add_i32 s4, s49, 32
	v_add_u32_e32 v0, 32, v206
	s_cmpk_gt_u32 s4, 0x7f
	v_max_u32_e32 v0, 0x70, v0
	v_add_u32_e32 v2, 0xffffffa0, v206
	v_add_u32_e32 v0, 0x3f90, v0
	s_cselect_b64 vcc, -1, 0
	v_cndmask_b32_e32 v0, v0, v2, vcc
	v_lshlrev_b64 v[2:3], 10, v[0:1]
	v_add_u32_e32 v0, 32, v207
	v_max_u32_e32 v0, 0x70, v0
	v_add_u32_e32 v4, 0xffffffa0, v207
	v_add_u32_e32 v0, 0x3f90, v0
	v_cndmask_b32_e32 v0, v0, v4, vcc
	v_lshlrev_b64 v[4:5], 10, v[0:1]
	v_lshl_add_u64 v[4:5], v[196:197], 0, v[4:5]
	v_lshl_add_u64 v[2:3], v[194:195], 0, v[2:3]
	global_load_dwordx4 v[118:121], v[4:5], off offset:48
	global_load_dwordx4 v[126:129], v[4:5], off offset:32
	global_load_dwordx4 v[130:133], v[4:5], off offset:16
	global_load_dwordx4 v[134:137], v[4:5], off
	v_mov_b32_e32 v222, s4
	v_lshlrev_b32_e32 v222, 7, v222
	v_mov_b32_e32 v223, 0
	v_lshl_add_u64 v[220:221], v[218:219], 0, v[222:223]
	global_load_dwordx4 v[90:93], v[220:221], off
	global_load_dwordx4 v[94:97], v[220:221], off offset:1024
	global_load_dwordx4 v[86:89], v[220:221], off offset:2048
	global_load_dwordx4 v[82:85], v[220:221], off offset:3072
	v_exp_f32_e64 v0, -v208
	s_cmpk_lt_u32 s50, 0xa0
	s_cselect_b64 s[26:27], -1, 0
	s_cmpk_gt_u32 s50, 0x9f
	s_mov_b64 s[4:5], -1
	s_waitcnt vmcnt(24)
	ds_write_b128 v199, v[158:161]
	ds_write_b128 v199, v[154:157] offset:16
	ds_write_b128 v199, v[150:153] offset:32
	ds_write_b128 v199, v[146:149] offset:48
	s_cbranch_scc0 .LBB0_1053
; #define LAS __attribute__((address_space(3)))
; __device__ __forceinline__ unsigned cvtpk_s(float lo, float hi) { f32x2_t v = {lo, hi}; bf16x2_t b = __builtin_convertvector(v, bf16x2_t); return __builtin_bit_cast(unsigned, b); }
; template <bool MASK> __device__ __forceinline__ void sb_tile(const SbTile& t0, const bf16x8 (&qf)[4], f32x16& o0, f32x16& o1, float& carry, int kt, int qpos, int hi, LAS unsigned char* vw, const LAS unsigned char* vr) {
; #pragma unroll
;     for (int j = 0; j < 4; ++j) *(LAS u32x4*)(vw + 16 * j) = t0.v[j];
;     f32x16 z;
; #pragma unroll
;     for (int r = 0; r < 16; ++r) z[r] = 0.f;
; #pragma unroll
;     for (int j = 0; j < 4; ++j) z = MFMA32(t0.k[j], qf[j], z);
;     float kp[16], bt[16];
; #pragma unroll
;     for (int r = 0; r < 16; ++r) { const float e = __builtin_amdgcn_exp2f(z[r]); const float k = __builtin_amdgcn_rcpf(1.0f + e); const float b = e * k;
;         if (MASK) { const int kpos = kt + crow(r, hi); const bool okr = (kpos < qpos) && (kpos >= 112); kp[r] = okr ? k : 1.0f; bt[r] = okr ? b : 0.f; } else { kp[r] = k; bt[r] = b; } }
;     float G[4], Go[4];
; #pragma unroll
;     for (int g = 0; g < 4; ++g) { G[g] = (kp[4 * g] * kp[4 * g + 1]) * (kp[4 * g + 2] * kp[4 * g + 3]); Go[g] = __shfl_xor(G[g], 32); }
;     const float c0 = __builtin_amdgcn_exp2f(-carry);
;     float offs[4]; float T = 1.0f;
; #pragma unroll
;     for (int g = 3; g >= 0; --g) { offs[g] = c0 * T * (hi == 0 ? Go[g] : 1.0f); T *= G[g] * Go[g]; }
;     f32x16 w;
; #pragma unroll
;     for (int g = 0; g < 4; ++g) { float run = offs[g];
; #pragma unroll
;         for (int i = 3; i >= 0; --i) { const int r = 4 * g + i; w[r] = bt[r] * run; run *= kp[r]; } }
;     carry -= __builtin_amdgcn_logf(T);
; #pragma unroll
;     for (int s = 0; s < 2; ++s) { u32x4 wp;
; #pragma unroll
;         for (int i = 0; i < 4; ++i) wp[i] = cvtpk_s(w[8 * s + 2 * i], w[8 * s + 2 * i + 1]);
;         const bf16x8 wb = __builtin_bit_cast(bf16x8, wp);
;         const s16x4 a0 = vtr(vr + (16 * s) * 144), a1 = vtr(vr + (16 * s + 8) * 144), b0 = vtr(vr + (16 * s) * 144 + 64), b1 = vtr(vr + (16 * s + 8) * 144 + 64);
;         const bf16x8 v0 = __builtin_shufflevector(a0, a1, 0, 1, 2, 3, 4, 5, 6, 7), v1 = __builtin_shufflevector(b0, b1, 0, 1, 2, 3, 4, 5, 6, 7);
;         o0 = MFMA32(v0, wb, o0); o1 = MFMA32(v1, wb, o1); }
; }
	s_waitcnt vmcnt(19)
	v_mfma_f32_32x32x16_bf16 v[2:17], v[102:105], v[66:69], 0
	s_mov_b64 s[4:5], 0
	s_waitcnt vmcnt(18)
	v_mfma_f32_32x32x16_bf16 v[2:17], v[110:113], v[70:73], v[2:17]
	s_waitcnt vmcnt(17)
	v_mfma_f32_32x32x16_bf16 v[2:17], v[106:109], v[74:77], v[2:17]
	s_waitcnt vmcnt(16)
	v_mfma_f32_32x32x16_bf16 v[2:17], v[98:101], v[78:81], v[2:17]
	s_nop 11
	v_exp_f32_e32 v7, v7
	v_exp_f32_e32 v8, v8
	v_exp_f32_e32 v9, v9
	v_exp_f32_e32 v10, v10
	v_exp_f32_e32 v12, v12
	v_exp_f32_e32 v13, v13
	v_exp_f32_e32 v30, v14
	v_add_f32_e32 v23, 1.0, v7
	v_add_f32_e32 v25, 1.0, v8
	v_add_f32_e32 v26, 1.0, v9
	v_add_f32_e32 v27, 1.0, v10
	v_add_f32_e32 v29, 1.0, v12
	v_add_f32_e32 v14, 1.0, v13
	v_rcp_f32_e32 v24, v23
	v_rcp_f32_e32 v23, v25
	v_rcp_f32_e32 v25, v26
	v_rcp_f32_e32 v26, v27
	v_rcp_f32_e32 v27, v29
	v_rcp_f32_e32 v29, v14
	v_exp_f32_e32 v31, v15
	v_add_f32_e32 v14, 1.0, v30
	v_rcp_f32_e32 v32, v14
	v_exp_f32_e32 v14, v16
	v_exp_f32_e32 v15, v17
	v_exp_f32_e32 v11, v11
	v_add_f32_e32 v16, 1.0, v31
	v_exp_f32_e32 v6, v6
	v_rcp_f32_e32 v154, v16
	v_add_f32_e32 v16, 1.0, v14
	v_rcp_f32_e32 v33, v16
	v_add_f32_e32 v16, 1.0, v15
	v_add_f32_e32 v28, 1.0, v11
	v_rcp_f32_e32 v155, v16
	v_rcp_f32_e32 v28, v28
	v_add_f32_e32 v22, 1.0, v6
	v_and_b32_e32 v17, 64, v201
	v_exp_f32_e32 v4, v4
	v_exp_f32_e32 v5, v5
	v_rcp_f32_e32 v22, v22
	v_xor_b32_e32 v16, 32, v201
	v_add_u32_e32 v17, 64, v17
	v_exp_f32_e32 v2, v2
	v_exp_f32_e32 v3, v3
	v_cmp_lt_i32_e32 vcc, v16, v17
	v_pk_mul_f32 v[146:147], v[32:33], v[154:155]
	v_add_f32_e32 v20, 1.0, v4
	v_cndmask_b32_e32 v16, v201, v16, vcc
	v_mul_f32_e32 v148, v146, v147
	v_pk_mul_f32 v[146:147], v[26:27], v[28:29]
	v_lshlrev_b32_e32 v150, 2, v16
	v_mul_f32_e32 v146, v146, v147
	v_add_f32_e32 v21, 1.0, v5
	v_pk_mul_f32 v[16:17], v[22:23], v[24:25]
	ds_bpermute_b32 v149, v150, v148
	ds_bpermute_b32 v151, v150, v146
	v_add_f32_e32 v18, 1.0, v2
	v_add_f32_e32 v19, 1.0, v3
	v_rcp_f32_e32 v20, v20
	v_rcp_f32_e32 v21, v21
	v_pk_mul_f32 v[16:17], v[16:17], v[16:17] op_sel:[0,1] op_sel_hi:[1,0]
	v_rcp_f32_e32 v18, v18
	v_rcp_f32_e32 v19, v19
	ds_bpermute_b32 v17, v150, v16
	s_waitcnt lgkmcnt(2)
	v_cndmask_b32_e64 v152, 1.0, v149, s[0:1]
	v_mul_f32_e32 v147, v148, v149
	s_waitcnt lgkmcnt(1)
	v_mul_f32_e32 v149, v146, v151
	v_mov_b32_e32 v146, v20
	v_mov_b32_e32 v148, v21
	v_mul_f32_e32 v153, v0, v147
	v_pk_mul_f32 v[146:147], v[146:147], v[148:149]
	v_mov_b32_e32 v148, v18
	v_mov_b32_e32 v149, v16
	v_mov_b32_e32 v16, v19
	v_cndmask_b32_e64 v156, 1.0, v151, s[0:1]
	s_waitcnt lgkmcnt(0)
	v_cndmask_b32_e64 v151, 1.0, v17, s[0:1]
	v_pk_mul_f32 v[16:17], v[148:149], v[16:17]
	v_pk_mul_f32 v[4:5], v[4:5], v[20:21]
	v_pk_mul_f32 v[210:211], v[16:17], v[146:147]
	ds_bpermute_b32 v209, v150, v210
	v_mul_f32_e32 v16, v0, v211
	v_pk_mul_f32 v[2:3], v[2:3], v[18:19]
	v_mul_f32_e32 v146, v0, v147
	v_mov_b32_e32 v18, v22
	s_waitcnt lgkmcnt(0)
	v_cndmask_b32_e64 v17, 1.0, v209, s[0:1]
	v_mul_f32_e32 v17, v17, v16
	v_mul_f32_e32 v16, v21, v17
	v_pk_mul_f32 v[4:5], v[4:5], v[16:17]
	v_mul_f32_e32 v17, v20, v16
	v_mul_f32_e32 v16, v19, v17
	v_pk_mul_f32 v[2:3], v[2:3], v[16:17]
	v_mov_b32_e32 v16, v23
	v_mov_b32_e32 v17, v25
	v_pk_mul_f32 v[8:9], v[8:9], v[16:17]
	v_mul_f32_e32 v17, v151, v146
	v_mul_f32_e32 v16, v25, v17
	v_pk_mul_f32 v[8:9], v[8:9], v[16:17]
	v_mov_b32_e32 v19, v24
	v_mul_f32_e32 v17, v23, v16
	v_pk_mul_f32 v[6:7], v[6:7], v[18:19]
	v_mul_f32_e32 v16, v24, v17
	v_pk_mul_f32 v[6:7], v[6:7], v[16:17]
	v_mov_b32_e32 v16, v27
	v_mov_b32_e32 v17, v29
	v_pk_mul_f32 v[12:13], v[12:13], v[16:17]
	v_mul_f32_e32 v17, v156, v153
	v_mul_f32_e32 v16, v29, v17
	v_pk_mul_f32 v[158:159], v[12:13], v[16:17]
	v_mov_b32_e32 v12, v26
	v_mov_b32_e32 v13, v28
	ds_read_b64_tr_b16 v[18:19], v200
	ds_read_b64_tr_b16 v[20:21], v200 offset:1152
	v_pk_mul_f32 v[10:11], v[10:11], v[12:13]
	v_mul_f32_e32 v13, v27, v16
	v_mul_f32_e32 v23, v0, v152
	ds_read_b64_tr_b16 v[152:153], v200 offset:1216
	ds_read_b64_tr_b16 v[150:151], v200 offset:64
	v_mul_f32_e32 v12, v28, v13
	v_pk_mul_f32 v[160:161], v[10:11], v[12:13]
	v_mov_b32_e32 v10, v33
	v_mov_b32_e32 v11, v155
	v_pk_mul_f32 v[10:11], v[14:15], v[10:11]
	v_mul_f32_e32 v22, v155, v23
	v_cvt_pk_bf16_f32 v146, v2, v3
	v_cvt_pk_bf16_f32 v147, v4, v5
	v_cvt_pk_bf16_f32 v148, v6, v7
	v_cvt_pk_bf16_f32 v149, v8, v9
	v_pk_mul_f32 v[212:213], v[10:11], v[22:23]
	v_mul_f32_e32 v217, v33, v22
	s_waitcnt lgkmcnt(2)
	v_mfma_f32_32x32x16_bf16 v[2:17], v[18:21], v[146:149], v[34:49]
	v_mov_b32_e32 v18, v32
	v_mov_b32_e32 v19, v154
	v_mul_f32_e64 v214, v30, v18
	v_mul_f32_e64 v215, v31, v19
	v_mul_f32_e32 v216, v154, v217
	ds_read_b64_tr_b16 v[154:155], v200 offset:2304
	ds_read_b64_tr_b16 v[156:157], v200 offset:3456
	s_waitcnt lgkmcnt(2)
	v_mfma_f32_32x32x16_bf16 v[18:33], v[150:153], v[146:149], v[50:65]
	v_cvt_pk_bf16_f32 v148, v160, v161
	v_cvt_pk_bf16_f32 v149, v158, v159
	ds_read_b64_tr_b16 v[160:161], v200 offset:3520
	ds_read_b64_tr_b16 v[158:159], v200 offset:2368
	v_mul_f32_e64 v146, v214, v216
	v_mul_f32_e64 v147, v215, v217
	v_cvt_pk_bf16_f32 v151, v212, v213
	v_cvt_pk_bf16_f32 v150, v146, v147
	v_mul_f32_e32 v146, v210, v209
	v_mul_f32_e32 v146, v146, v211
	s_waitcnt lgkmcnt(2)
	v_mfma_f32_32x32x16_bf16 v[2:17], v[154:157], v[148:151], v[2:17]
	v_log_f32_e32 v146, v146
	s_waitcnt lgkmcnt(0)
	v_mfma_f32_32x32x16_bf16 v[18:33], v[158:161], v[148:151], v[18:33]

; __device__ __forceinline__ void sb_load(SbTile& t, const bf16* SK, const bf16* SV, int h, int kt, int lane) {
;     const bf16* kp = SK + (size_t)pos2row(kt + (lane & 31)) * 512 + h * 64 + 8 * (lane >> 5);
;     const bf16* vp = SV + (size_t)pos2row(kt + (lane >> 1)) * 512 + h * 64 + 32 * (lane & 1);
; #pragma unroll
;     for (int j = 0; j < 4; ++j) { t.k[j] = *(const bf16x8*)(kp + 16 * j); t.v[j] = *(const u32x4*)(vp + 8 * j); }
; }
.LBB0_1055:
	v_sub_f32_e32 v208, v208, v146
	v_cmp_lt_f32_e32 vcc, s45, v208
	s_cmp_eq_u64 vcc, exec
	s_cselect_b64 s[4:5], -1, 0
	s_or_b64 s[6:7], s[26:27], s[4:5]
	s_mov_b64 s[4:5], -1
	s_and_b64 vcc, exec, s[6:7]
	s_cbranch_vccnz .LBB0_1061
	s_cmpk_gt_u32 s49, 0x7f
	v_max_u32_e32 v34, 0x70, v206
	v_add_u32_e32 v0, 0xffffff80, v206
	v_add_u32_e32 v34, 0x3f90, v34
	s_cselect_b64 vcc, -1, 0
	v_cndmask_b32_e32 v0, v34, v0, vcc
	v_max_u32_e32 v36, 0x70, v207
	v_lshlrev_b64 v[34:35], 10, v[0:1]
	v_add_u32_e32 v0, 0xffffff80, v207
	v_add_u32_e32 v36, 0x3f90, v36
	v_cndmask_b32_e32 v0, v36, v0, vcc
	v_lshlrev_b64 v[36:37], 10, v[0:1]
	v_lshl_add_u64 v[36:37], v[196:197], 0, v[36:37]
	v_lshl_add_u64 v[34:35], v[194:195], 0, v[34:35]
	global_load_dwordx4 v[146:149], v[36:37], off offset:48
	global_load_dwordx4 v[150:153], v[36:37], off offset:32
	global_load_dwordx4 v[154:157], v[36:37], off offset:16
	global_load_dwordx4 v[158:161], v[36:37], off
	v_mov_b32_e32 v222, s49
	v_lshlrev_b32_e32 v222, 7, v222
	v_mov_b32_e32 v223, 0
	v_lshl_add_u64 v[220:221], v[218:219], 0, v[222:223]
	global_load_dwordx4 v[102:105], v[220:221], off
	global_load_dwordx4 v[110:113], v[220:221], off offset:1024
	global_load_dwordx4 v[106:109], v[220:221], off offset:2048
	global_load_dwordx4 v[98:101], v[220:221], off offset:3072
	v_exp_f32_e64 v0, -v208
	s_cmpk_lt_u32 s50, 0xc0
	s_cselect_b64 s[14:15], -1, 0
	s_cmpk_gt_u32 s50, 0xbf
	s_waitcnt vmcnt(20)
	ds_write_b128 v199, v[174:177]
	ds_write_b128 v199, v[170:173] offset:16
	ds_write_b128 v199, v[166:169] offset:32
	ds_write_b128 v199, v[162:165] offset:48
	s_cbranch_scc0 .LBB0_1058
; #define LAS __attribute__((address_space(3)))
; __device__ __forceinline__ unsigned cvtpk_s(float lo, float hi) { f32x2_t v = {lo, hi}; bf16x2_t b = __builtin_convertvector(v, bf16x2_t); return __builtin_bit_cast(unsigned, b); }
; template <bool MASK> __device__ __forceinline__ void sb_tile(const SbTile& t0, const bf16x8 (&qf)[4], f32x16& o0, f32x16& o1, float& carry, int kt, int qpos, int hi, LAS unsigned char* vw, const LAS unsigned char* vr) {
; #pragma unroll
;     for (int j = 0; j < 4; ++j) *(LAS u32x4*)(vw + 16 * j) = t0.v[j];
;     f32x16 z;
; #pragma unroll
;     for (int r = 0; r < 16; ++r) z[r] = 0.f;
; #pragma unroll
;     for (int j = 0; j < 4; ++j) z = MFMA32(t0.k[j], qf[j], z);
;     float kp[16], bt[16];
; #pragma unroll
;     for (int r = 0; r < 16; ++r) { const float e = __builtin_amdgcn_exp2f(z[r]); const float k = __builtin_amdgcn_rcpf(1.0f + e); const float b = e * k;
;         if (MASK) { const int kpos = kt + crow(r, hi); const bool okr = (kpos < qpos) && (kpos >= 112); kp[r] = okr ? k : 1.0f; bt[r] = okr ? b : 0.f; } else { kp[r] = k; bt[r] = b; } }
;     float G[4], Go[4];
; #pragma unroll
;     for (int g = 0; g < 4; ++g) { G[g] = (kp[4 * g] * kp[4 * g + 1]) * (kp[4 * g + 2] * kp[4 * g + 3]); Go[g] = __shfl_xor(G[g], 32); }
;     const float c0 = __builtin_amdgcn_exp2f(-carry);
;     float offs[4]; float T = 1.0f;
; #pragma unroll
;     for (int g = 3; g >= 0; --g) { offs[g] = c0 * T * (hi == 0 ? Go[g] : 1.0f); T *= G[g] * Go[g]; }
;     f32x16 w;
; #pragma unroll
;     for (int g = 0; g < 4; ++g) { float run = offs[g];
; #pragma unroll
;         for (int i = 3; i >= 0; --i) { const int r = 4 * g + i; w[r] = bt[r] * run; run *= kp[r]; } }
;     carry -= __builtin_amdgcn_logf(T);
; #pragma unroll
;     for (int s = 0; s < 2; ++s) { u32x4 wp;
; #pragma unroll
;         for (int i = 0; i < 4; ++i) wp[i] = cvtpk_s(w[8 * s + 2 * i], w[8 * s + 2 * i + 1]);
;         const bf16x8 wb = __builtin_bit_cast(bf16x8, wp);
;         const s16x4 a0 = vtr(vr + (16 * s) * 144), a1 = vtr(vr + (16 * s + 8) * 144), b0 = vtr(vr + (16 * s) * 144 + 64), b1 = vtr(vr + (16 * s + 8) * 144 + 64);
;         const bf16x8 v0 = __builtin_shufflevector(a0, a1, 0, 1, 2, 3, 4, 5, 6, 7), v1 = __builtin_shufflevector(b0, b1, 0, 1, 2, 3, 4, 5, 6, 7);
;         o0 = MFMA32(v0, wb, o0); o1 = MFMA32(v1, wb, o1); }
; }
	s_waitcnt vmcnt(19)
	v_mfma_f32_32x32x16_bf16 v[34:49], v[142:145], v[66:69], 0
	s_mov_b64 s[4:5], 0
	s_waitcnt vmcnt(18)
	v_mfma_f32_32x32x16_bf16 v[34:49], v[138:141], v[70:73], v[34:49]
	s_waitcnt vmcnt(17)
	v_mfma_f32_32x32x16_bf16 v[34:49], v[122:125], v[74:77], v[34:49]
	s_waitcnt vmcnt(16)
	v_mfma_f32_32x32x16_bf16 v[34:49], v[114:117], v[78:81], v[34:49]
	s_nop 11
	v_exp_f32_e32 v39, v39
	v_exp_f32_e32 v40, v40
	v_exp_f32_e32 v41, v41
	v_exp_f32_e32 v42, v42
	v_exp_f32_e32 v44, v44
	v_exp_f32_e32 v45, v45
	v_exp_f32_e32 v62, v46
	v_add_f32_e32 v55, 1.0, v39
	v_add_f32_e32 v57, 1.0, v40
	v_add_f32_e32 v58, 1.0, v41
	v_add_f32_e32 v59, 1.0, v42
	v_add_f32_e32 v61, 1.0, v44
	v_add_f32_e32 v46, 1.0, v45
	v_rcp_f32_e32 v56, v55
	v_rcp_f32_e32 v55, v57
	v_rcp_f32_e32 v57, v58
	v_rcp_f32_e32 v58, v59
	v_rcp_f32_e32 v59, v61
	v_rcp_f32_e32 v61, v46
	v_exp_f32_e32 v63, v47
	v_add_f32_e32 v46, 1.0, v62
	v_rcp_f32_e32 v64, v46
	v_exp_f32_e32 v46, v48
	v_exp_f32_e32 v47, v49
	v_exp_f32_e32 v43, v43
	v_add_f32_e32 v48, 1.0, v63
	v_exp_f32_e32 v38, v38
	v_rcp_f32_e32 v170, v48
	v_add_f32_e32 v48, 1.0, v46
	v_rcp_f32_e32 v65, v48
	v_add_f32_e32 v48, 1.0, v47
	v_add_f32_e32 v60, 1.0, v43
	v_rcp_f32_e32 v171, v48
	v_rcp_f32_e32 v60, v60
	v_add_f32_e32 v54, 1.0, v38
	v_and_b32_e32 v49, 64, v201
	v_exp_f32_e32 v36, v36
	v_exp_f32_e32 v37, v37
	v_rcp_f32_e32 v54, v54
	v_xor_b32_e32 v48, 32, v201
	v_add_u32_e32 v49, 64, v49
	v_exp_f32_e32 v34, v34
	v_exp_f32_e32 v35, v35
	v_cmp_lt_i32_e32 vcc, v48, v49
	v_pk_mul_f32 v[162:163], v[64:65], v[170:171]
	v_add_f32_e32 v52, 1.0, v36
	v_cndmask_b32_e32 v48, v201, v48, vcc
	v_mul_f32_e32 v164, v162, v163
	v_pk_mul_f32 v[162:163], v[58:59], v[60:61]
	v_lshlrev_b32_e32 v166, 2, v48
	v_mul_f32_e32 v162, v162, v163
	v_add_f32_e32 v53, 1.0, v37
	v_pk_mul_f32 v[48:49], v[54:55], v[56:57]
	ds_bpermute_b32 v165, v166, v164
	ds_bpermute_b32 v167, v166, v162
	v_add_f32_e32 v50, 1.0, v34
	v_add_f32_e32 v51, 1.0, v35
	v_rcp_f32_e32 v52, v52
	v_rcp_f32_e32 v53, v53
	v_pk_mul_f32 v[48:49], v[48:49], v[48:49] op_sel:[0,1] op_sel_hi:[1,0]
	v_rcp_f32_e32 v50, v50
	v_rcp_f32_e32 v51, v51
	ds_bpermute_b32 v49, v166, v48
	s_waitcnt lgkmcnt(2)
	v_cndmask_b32_e64 v168, 1.0, v165, s[0:1]
	v_mul_f32_e32 v163, v164, v165
	s_waitcnt lgkmcnt(1)
	v_mul_f32_e32 v165, v162, v167
	v_mov_b32_e32 v162, v52
	v_mov_b32_e32 v164, v53
	v_mul_f32_e32 v169, v0, v163
	v_pk_mul_f32 v[162:163], v[162:163], v[164:165]
	v_mov_b32_e32 v164, v50
	v_mov_b32_e32 v165, v48
	v_mov_b32_e32 v48, v51
	v_cndmask_b32_e64 v172, 1.0, v167, s[0:1]
	s_waitcnt lgkmcnt(0)
	v_cndmask_b32_e64 v167, 1.0, v49, s[0:1]
	v_pk_mul_f32 v[48:49], v[164:165], v[48:49]
	v_pk_mul_f32 v[36:37], v[36:37], v[52:53]
	v_pk_mul_f32 v[206:207], v[48:49], v[162:163]
	ds_bpermute_b32 v209, v166, v206
	v_mul_f32_e32 v48, v0, v207
	v_pk_mul_f32 v[34:35], v[34:35], v[50:51]
	v_mul_f32_e32 v162, v0, v163
	v_mov_b32_e32 v50, v54
	s_waitcnt lgkmcnt(0)
	v_cndmask_b32_e64 v49, 1.0, v209, s[0:1]
	v_mul_f32_e32 v49, v49, v48
	v_mul_f32_e32 v48, v53, v49
	v_pk_mul_f32 v[36:37], v[36:37], v[48:49]
	v_mul_f32_e32 v49, v52, v48
	v_mul_f32_e32 v48, v51, v49
	v_pk_mul_f32 v[34:35], v[34:35], v[48:49]
	v_mov_b32_e32 v48, v55
	v_mov_b32_e32 v49, v57
	v_pk_mul_f32 v[40:41], v[40:41], v[48:49]
	v_mul_f32_e32 v49, v167, v162
	v_mul_f32_e32 v48, v57, v49
	v_pk_mul_f32 v[40:41], v[40:41], v[48:49]
	v_mov_b32_e32 v51, v56
	v_mul_f32_e32 v49, v55, v48
	v_pk_mul_f32 v[38:39], v[38:39], v[50:51]
	v_mul_f32_e32 v48, v56, v49
	v_pk_mul_f32 v[38:39], v[38:39], v[48:49]
	v_mov_b32_e32 v48, v59
	v_mov_b32_e32 v49, v61
	v_pk_mul_f32 v[44:45], v[44:45], v[48:49]
	v_mul_f32_e32 v49, v172, v169
	v_mul_f32_e32 v48, v61, v49
	v_pk_mul_f32 v[174:175], v[44:45], v[48:49]
	v_mov_b32_e32 v44, v58
	v_mov_b32_e32 v45, v60
	ds_read_b64_tr_b16 v[50:51], v200
	ds_read_b64_tr_b16 v[52:53], v200 offset:1152
	v_pk_mul_f32 v[42:43], v[42:43], v[44:45]
	v_mul_f32_e32 v45, v59, v48
	v_mul_f32_e32 v55, v0, v168
	ds_read_b64_tr_b16 v[168:169], v200 offset:1216
	ds_read_b64_tr_b16 v[166:167], v200 offset:64
	v_mul_f32_e32 v44, v60, v45
	v_pk_mul_f32 v[176:177], v[42:43], v[44:45]
	v_mov_b32_e32 v42, v65
	v_mov_b32_e32 v43, v171
	v_pk_mul_f32 v[42:43], v[46:47], v[42:43]
	v_mul_f32_e32 v54, v171, v55
	v_cvt_pk_bf16_f32 v162, v34, v35
	v_cvt_pk_bf16_f32 v163, v36, v37
	v_cvt_pk_bf16_f32 v164, v38, v39
	v_cvt_pk_bf16_f32 v165, v40, v41
	v_pk_mul_f32 v[210:211], v[42:43], v[54:55]
	v_mul_f32_e32 v215, v65, v54
	s_waitcnt lgkmcnt(2)
	v_mfma_f32_32x32x16_bf16 v[34:49], v[50:53], v[162:165], v[2:17]
	v_mov_b32_e32 v50, v64
	v_mov_b32_e32 v51, v170
	v_mul_f32_e64 v212, v62, v50
	v_mul_f32_e64 v213, v63, v51
	v_mul_f32_e32 v214, v170, v215
	ds_read_b64_tr_b16 v[170:171], v200 offset:2304
	ds_read_b64_tr_b16 v[172:173], v200 offset:3456
	s_waitcnt lgkmcnt(2)
	v_mfma_f32_32x32x16_bf16 v[50:65], v[166:169], v[162:165], v[18:33]
	v_cvt_pk_bf16_f32 v164, v176, v177
	v_cvt_pk_bf16_f32 v165, v174, v175
	ds_read_b64_tr_b16 v[176:177], v200 offset:3520
	ds_read_b64_tr_b16 v[174:175], v200 offset:2368
	v_mul_f32_e64 v162, v212, v214
	v_mul_f32_e64 v163, v213, v215
	v_cvt_pk_bf16_f32 v167, v210, v211
	v_cvt_pk_bf16_f32 v166, v162, v163
	v_mul_f32_e32 v162, v206, v209
	v_mul_f32_e32 v162, v162, v207
	s_waitcnt lgkmcnt(2)
	v_mfma_f32_32x32x16_bf16 v[34:49], v[170:173], v[164:167], v[34:49]
	v_log_f32_e32 v162, v162
	s_waitcnt lgkmcnt(0)
	v_mfma_f32_32x32x16_bf16 v[50:65], v[174:177], v[164:167], v[50:65]

; __global__ void __launch_bounds__(NT, 2) hymba_fwd(Args args) {
	.amdhsa_kernel _Z9hymba_fwd4Args
		.amdhsa_group_segment_fixed_size 0
		.amdhsa_private_segment_fixed_size 0
		.amdhsa_kernarg_size 408
		.amdhsa_user_sgpr_count 2
		.amdhsa_user_sgpr_dispatch_ptr 0
		.amdhsa_user_sgpr_queue_ptr 0
		.amdhsa_user_sgpr_kernarg_segment_ptr 1
		.amdhsa_user_sgpr_dispatch_id 0
		.amdhsa_user_sgpr_kernarg_preload_length 0
		.amdhsa_user_sgpr_kernarg_preload_offset 0
		.amdhsa_user_sgpr_private_segment_size 0
		.amdhsa_uses_dynamic_stack 0
		.amdhsa_enable_private_segment 0
		.amdhsa_system_sgpr_workgroup_id_x 1
		.amdhsa_system_sgpr_workgroup_id_y 0
		.amdhsa_system_sgpr_workgroup_id_z 0
		.amdhsa_system_sgpr_workgroup_info 0
		.amdhsa_system_vgpr_workitem_id 2
		.amdhsa_next_free_vgpr 245
		.amdhsa_next_free_sgpr 102
		.amdhsa_accum_offset 240
		.amdhsa_reserve_vcc 1
		.amdhsa_float_round_mode_32 0
		.amdhsa_float_round_mode_16_64 0
		.amdhsa_float_denorm_mode_32 3
		.amdhsa_float_denorm_mode_16_64 3
		.amdhsa_dx10_clamp 1
		.amdhsa_ieee_mode 1
		.amdhsa_fp16_overflow 0
		.amdhsa_tg_split 0
		.amdhsa_exception_fp_ieee_invalid_op 0
		.amdhsa_exception_fp_denorm_src 0
		.amdhsa_exception_fp_ieee_div_zero 0
		.amdhsa_exception_fp_ieee_overflow 0
		.amdhsa_exception_fp_ieee_underflow 0
		.amdhsa_exception_fp_ieee_inexact 0
		.amdhsa_exception_int_div_zero 0
	.end_amdhsa_kernel

; __global__ void __launch_bounds__(NT, 2) hymba_fwd(Args args) {
amdhsa.kernels:
  - .agpr_count:     5
    .args:
      - .offset:         0
        .size:           152
        .value_kind:     by_value
      - .offset:         152
        .size:           4
        .value_kind:     hidden_block_count_x
      - .offset:         156
        .size:           4
        .value_kind:     hidden_block_count_y
      - .offset:         160
        .size:           4
        .value_kind:     hidden_block_count_z
      - .offset:         164
        .size:           2
        .value_kind:     hidden_group_size_x
      - .offset:         166
        .size:           2
        .value_kind:     hidden_group_size_y
      - .offset:         168
        .size:           2
        .value_kind:     hidden_group_size_z
      - .offset:         170
        .size:           2
        .value_kind:     hidden_remainder_x
      - .offset:         172
        .size:           2
        .value_kind:     hidden_remainder_y
      - .offset:         174
        .size:           2
        .value_kind:     hidden_remainder_z
      - .offset:         192
        .size:           8
        .value_kind:     hidden_global_offset_x
      - .offset:         200
        .size:           8
        .value_kind:     hidden_global_offset_y
      - .offset:         208
        .size:           8
        .value_kind:     hidden_global_offset_z
      - .offset:         216
        .size:           2
        .value_kind:     hidden_grid_dims
      - .offset:         240
        .size:           8
        .value_kind:     hidden_multigrid_sync_arg
      - .offset:         272
        .size:           4
        .value_kind:     hidden_dynamic_lds_size
    .group_segment_fixed_size: 0
    .kernarg_segment_align: 8
    .kernarg_segment_size: 408
    .language:       OpenCL C
    .language_version:
      - 2
      - 0
    .max_flat_workgroup_size: 512
    .name:           _Z9hymba_fwd4Args
    .private_segment_fixed_size: 0
    .sgpr_count:     108
    .sgpr_spill_count: 133
    .symbol:         _Z9hymba_fwd4Args.kd
    .uniform_work_group_size: 1
    .uses_dynamic_stack: false
    .vgpr_count:     238
    .vgpr_spill_count: 0
    .wavefront_size: 64
